# attention: softmax scale*log2e folded into q before its bf16 rounding (token passes) and -mfix into the QK accumulator init; per-element scale FMAs deleted
# speedup vs baseline: 1.0595x; 1.0274x over previous
; template <int DQK, bool MIXA, bool PIPE>
; DI void attn_item(const Params& P, int layer, char* smem, int b, int h, int qt) {
;     ...
;     const float* g1 = MIXA ? (P.a_q_norm + layer * 64) : (P.b_q_norm + layer * 96);
;     const float* g2 = MIXA ? (P.a_k_norm + layer * 64) : (P.b_k_norm + layer * 96);
;     float a1 = 0.f, a2 = 0.f;
;     for (int i = 0; i < DQK; ++i) { a1 = fmaxf(a1, fabsf(g1[i])); a2 = fmaxf(a2, fabsf(g2[i])); }
;     mfix = (float)DQK * 1.02f * a1 * a2 * sl2;
.LBB0_84:
	s_add_u32 s20, s65, s18
	s_addc_u32 s21, s66, s19
	global_load_dwordx4 v[4:7], v137, s[20:21] offset:32
	global_load_dwordx4 v[8:11], v137, s[20:21] offset:16
	global_load_dwordx4 v[12:15], v137, s[20:21]
	s_add_u32 s20, s67, s18
	s_addc_u32 s21, s68, s19
	global_load_dwordx4 v[16:19], v137, s[20:21]
	global_load_dwordx4 v[20:23], v137, s[20:21] offset:16
	global_load_dwordx4 v[24:27], v137, s[20:21] offset:32
	s_add_u32 s18, s18, 48
	s_addc_u32 s19, s19, 0
	s_cmpk_eq_i32 s18, 0x180
	s_waitcnt vmcnt(3)
	v_max3_f32 v2, v2, |v12|, |v13|
	s_waitcnt vmcnt(2)
	v_max3_f32 v1, v1, |v16|, |v17|
	v_max3_f32 v2, v2, |v14|, |v15|
	v_max3_f32 v1, v1, |v18|, |v19|
	v_max3_f32 v2, v2, |v8|, |v9|
	s_waitcnt vmcnt(1)
	v_max3_f32 v1, v1, |v20|, |v21|
	v_max3_f32 v2, v2, |v10|, |v11|
	v_max3_f32 v1, v1, |v22|, |v23|
	v_max3_f32 v2, v2, |v4|, |v5|
	s_waitcnt vmcnt(0)
	v_max3_f32 v1, v1, |v24|, |v25|
	v_max3_f32 v2, v2, |v6|, |v7|
	v_max3_f32 v1, v1, |v26|, |v27|
	s_cbranch_scc0 .LBB0_84
; template <int DQK, bool MIXA, bool PIPE>
; DI void attn_item(const Params& P, int layer, char* smem, int b, int h, int qt) {
;     ...
;   bf16x8 qf[NS];
; #pragma unroll
;   for (int s = 0; s < NS; ++s) qf[s] = *(const bf16x8*)(Qp + tokq * ldq + 16 * s + 8 * H);
;   const int nkt = 2 * qt + 2;
;   unsigned koff[NKI], voff[2];
; #pragma unroll
;   for (int i = 0; i < NKI; ++i) {
;     const int e = (w * NKI + i) * 64 + lane;
;     const int row = e / KCH, slot = e % KCH;
;     const int c = slot ^ (MIXA ? ((row >> 1) & 7) : ((row >> 2) & 3));
;     koff[i] = (unsigned)((row * ldk + c * 8) * 2);
;   }
; #pragma unroll
;   for (int i = 0; i < 2; ++i) {
;     const int e = (w * 2 + i) * 64 + lane;
;     const int row = e >> 3, slot = e & 7;
;     const int c = slot ^ ((row >> 1) & 7);
;     voff[i] = (unsigned)((row * S_ + c * 8) * 2);
;   }
;   unsigned mwn[2] = {0u, 0u};
;   auto issue_loads = [&](int kt) __attribute__((always_inline)) {
;     const char* kbp = (const char*)(Kp + (size_t)(kt * 64) * ldk);
;     const char* vbp = (const char*)(VT + kt * 64);
;     char* sk = smem + (kt & 1) * STG_B;
; #pragma unroll
;     for (int i = 0; i < NKI; ++i)
;       __builtin_amdgcn_global_load_lds((const unsigned*)(kbp + koff[i]), (unsigned*)(sk + (w * NKI + i) * 1024), 16, 0, 0);
; #pragma unroll
;     for (int i = 0; i < 2; ++i)
;       __builtin_amdgcn_global_load_lds((const unsigned*)(vbp + voff[i]), (unsigned*)(sk + KTILE_B + (w * 2 + i) * 1024), 16, 0, 0);
;     if (MIXA) {
;       if (kt <= cw) {
;         const unsigned* mp = mask + mask_base(b, cw) + (2 * kt) * 64 + (qpos & 63);
;         mwn[0] = mp[0]; mwn[1] = mp[64];
;       }
;     }
;   };
;   issue_loads(0);
;   f32x16 o[2];
; #pragma unroll
;   for (int d = 0; d < 2; ++d)
; #pragma unroll
;     for (int i = 0; i < 16; ++i) o[d][i] = 0.f;
;   float l = 0.f;
;   const int pr = (l31 & ~12) | ((l31 & 4) << 1) | ((l31 & 8) >> 1);
;   const int swk = MIXA ? ((pr >> 1) & 7) : ((pr >> 2) & 3), swv = (l31 >> 1) & 7;
;   asm volatile("s_waitcnt vmcnt(0)" ::: "memory");
;   __syncthreads();
	v_lshl_or_b32 v3, v35, 3, s87
	v_ashrrev_i32_e32 v18, 6, v0
	v_mul_u32_u24_e32 v136, 0x300000, v3
	v_lshlrev_b32_e32 v3, 7, v34
	v_lshl_add_u32 v12, v18, 5, v3
	v_and_b32_e32 v20, 31, v0
	v_readlane_b32 s0, v252, 57
	v_or_b32_e32 v10, v12, v20
	v_lshlrev_b32_e32 v6, 14, v35
	v_readlane_b32 s1, v252, 58
	v_ashrrev_i32_e32 v11, 31, v10
	v_mov_b32_e32 v7, v137
	v_mul_f32_e32 v2, 0x42c3d70a, v2
	v_lshl_add_u64 v[8:9], s[0:1], 0, v[136:137]
	v_lshl_add_u64 v[112:113], v[10:11], 0, v[6:7]
	v_mul_f32_e32 v1, v1, v2
	v_mov_b64_e32 v[2:3], s[62:63]
	s_movk_i32 s0, 0x600
	v_bfe_u32 v139, v0, 5, 1
	v_mad_u64_u32 v[2:3], s[18:19], v112, s0, v[2:3]
	v_mad_i32_i24 v3, v113, s0, v3
	v_lshlrev_b32_e32 v6, 4, v139
	v_lshl_add_u64 v[2:3], v[2:3], 0, v[6:7]
	v_and_b32_e32 v21, 63, v0
	global_load_dwordx4 v[84:87], v[2:3], off
	global_load_dwordx4 v[80:83], v[2:3], off offset:32
	global_load_dwordx4 v[76:79], v[2:3], off offset:64
	global_load_dwordx4 v[72:75], v[2:3], off offset:96
	global_load_dwordx4 v[68:71], v[2:3], off offset:128
	global_load_dwordx4 v[64:67], v[2:3], off offset:160
	v_mul_lo_u32 v2, v18, s72
	v_or_b32_e32 v3, v2, v21
	s_mov_b32 s0, 0x2aaaaaab
	v_mul_hi_i32 v2, v3, s0
	v_lshrrev_b32_e32 v6, 31, v2
	v_ashrrev_i32_e32 v2, 1, v2
	v_add_u32_e32 v2, v2, v6
	v_mul_lo_u32 v6, v2, 12
	v_sub_u32_e32 v6, v3, v6
	v_lshrrev_b32_e32 v7, 2, v2
	v_bitop3_b32 v6, v7, v6, 3 bitop3:0x6c
	v_mul_lo_u32 v2, v2, s72
	v_lshl_add_u32 v2, v6, 4, v2
	v_add_u32_e32 v6, 64, v3
	v_mul_hi_i32 v7, v6, s0
	v_lshrrev_b32_e32 v10, 31, v7
	v_ashrrev_i32_e32 v7, 1, v7
	v_add_u32_e32 v7, v7, v10
	v_mul_lo_u32 v10, v7, 12
	v_sub_u32_e32 v6, v6, v10
	v_lshrrev_b32_e32 v10, 2, v7
	v_bitop3_b32 v6, v10, v6, 3 bitop3:0x6c
	v_mul_lo_u32 v7, v7, s72
	v_add_u32_e32 v3, 0x80, v3
	v_lshl_add_u32 v6, v6, 4, v7
	v_mul_hi_i32 v7, v3, s0
	v_lshrrev_b32_e32 v10, 31, v7
	v_ashrrev_i32_e32 v7, 1, v7
	v_add_u32_e32 v7, v7, v10
	v_mul_lo_u32 v10, v7, 12
	v_sub_u32_e32 v3, v3, v10
	v_lshrrev_b32_e32 v10, 2, v7
	v_bitop3_b32 v3, v10, v3, 3 bitop3:0x6c
	v_mul_lo_u32 v7, v7, s72
	v_lshl_add_u32 v10, v3, 4, v7
	v_mul_f32_e32 v114, 0x3e16c740, v1
	v_lshl_or_b32 v1, v18, 7, v21
	v_lshlrev_b32_e32 v3, 4, v0
	v_lshlrev_b32_e32 v7, 12, v1
	v_bitop3_b32 v22, v21, s92, v3 bitop3:0x48
	v_or_b32_e32 v1, 64, v1
	v_ashrrev_i32_e32 v127, 6, v12
	v_and_or_b32 v12, v7, s25, v22
	v_lshlrev_b32_e32 v7, 12, v1
	v_bitop3_b32 v1, v1, s92, v3 bitop3:0x48
	s_movk_i32 s0, 0x8000
	v_lshlrev_b32_e32 v19, 24, v35
	v_and_or_b32 v14, v7, s0, v1
	v_readlane_b32 s0, v252, 59
	v_or_b32_e32 v4, s88, v19
	v_mov_b32_e32 v5, v137
	v_readlane_b32 s1, v252, 60
	v_mov_b32_e32 v3, v137
	v_lshl_add_u64 v[16:17], v[8:9], 0, v[2:3]
	v_lshl_add_u64 v[4:5], s[0:1], 0, v[4:5]
	s_movk_i32 s0, 0xc00
	v_mul_lo_u32 v132, v18, s0
	v_add_u32_e32 v1, 0x400, v132
	v_readfirstlane_b32 s18, v132
	s_mov_b32 m0, s18
	v_mov_b32_e32 v7, v137
	v_readfirstlane_b32 s18, v1
	v_add_u32_e32 v1, 0x800, v132
	v_lshlrev_b32_e32 v135, 11, v18
	global_load_lds_dwordx4 v[16:17], off
	v_lshl_add_u64 v[16:17], v[8:9], 0, v[6:7]
	s_mov_b32 m0, s18
	v_mov_b32_e32 v11, v137
	v_readfirstlane_b32 s18, v1
	v_add_u32_e32 v1, 0x3000, v135
	global_load_lds_dwordx4 v[16:17], off
	v_lshl_add_u64 v[8:9], v[8:9], 0, v[10:11]
	s_mov_b32 m0, s18
	v_mov_b32_e32 v13, v137
	v_readfirstlane_b32 s18, v1
	v_add_u32_e32 v1, 0x3400, v135
	global_load_lds_dwordx4 v[8:9], off
	v_lshl_add_u64 v[8:9], v[4:5], 0, v[12:13]
	s_mov_b32 m0, s18
	v_mov_b32_e32 v15, v137
	v_readfirstlane_b32 s18, v1
	global_load_lds_dwordx4 v[8:9], off
	v_lshl_add_u64 v[4:5], v[4:5], 0, v[14:15]
	s_mov_b32 m0, s18
	v_and_b32_e32 v1, 19, v0
	global_load_lds_dwordx4 v[4:5], off
	v_lshlrev_b32_e32 v4, 1, v0
	v_lshrrev_b32_e32 v5, 1, v0
	v_and_b32_e32 v4, 8, v4
	v_and_b32_e32 v8, 4, v5
	v_or3_b32 v1, v4, v1, v8
	v_lshrrev_b32_e32 v4, 2, v1
	v_mul_u32_u24_e32 v141, 0xc0, v1
	v_or_b32_e32 v1, 2, v139
	v_bitop3_b32 v1, v4, v1, 3 bitop3:0x6c
	v_lshlrev_b32_e32 v142, 4, v1
	v_or_b32_e32 v1, 4, v139
	v_bitop3_b32 v1, v4, v1, 3 bitop3:0x6c
	v_lshlrev_b32_e32 v143, 4, v1
	v_or_b32_e32 v1, 6, v139
	v_bitop3_b32 v1, v4, v1, 3 bitop3:0x6c
	v_lshlrev_b32_e32 v144, 4, v1
	v_or_b32_e32 v1, 8, v139
	v_bitop3_b32 v1, v4, v1, 3 bitop3:0x6c
	v_lshlrev_b32_e32 v145, 4, v1
	v_or_b32_e32 v1, 10, v139
	v_bfe_u32 v0, v0, 1, 3
	v_bitop3_b32 v1, v4, v1, 3 bitop3:0x6c
	v_lshlrev_b32_e32 v146, 4, v1
	v_bitop3_b32 v1, v139, v0, 4 bitop3:0x36
	v_lshlrev_b32_e32 v130, 4, v1
	v_bitop3_b32 v1, v139, v5, 7 bitop3:0x78
	v_bitop3_b32 v8, v4, v139, 3 bitop3:0x6c
	v_lshlrev_b32_e32 v134, 4, v1
	v_bitop3_b32 v1, v139, v0, 2 bitop3:0x36
	v_bitop3_b32 v0, v139, v0, 6 bitop3:0x36
	v_lshlrev_b32_e32 v4, 12, v21
	s_waitcnt vmcnt(0)
	v_lshlrev_b32_e32 v133, 4, v1
	v_lshlrev_b32_e32 v131, 4, v0
	v_or_b32_e32 v0, s86, v19
	v_mov_b32_e32 v1, v137
	s_mov_b64 s[18:19], 0x1d000080
	v_lshl_or_b32 v4, v18, 19, v4
	v_lshlrev_b32_e32 v128, 1, v34
	v_lshl_add_u64 v[0:1], v[0:1], 0, s[18:19]
	v_and_or_b32 v4, v4, s25, v22
	v_mov_b32_e32 v5, v137
	v_or_b32_e32 v136, 0x18003000, v136
	v_mov_b32_e32 v126, 0
	v_lshlrev_b32_e32 v129, 7, v20
	v_mov_b32_e32 v115, v114
	v_sub_f32_e32 v228, 0, v114
	v_sub_f32_e32 v229, 0, v114
	v_sub_f32_e32 v230, 0, v114
	v_sub_f32_e32 v231, 0, v114
	v_sub_f32_e32 v232, 0, v114
	v_sub_f32_e32 v233, 0, v114
	v_sub_f32_e32 v234, 0, v114
	v_sub_f32_e32 v235, 0, v114
	v_sub_f32_e32 v236, 0, v114
	v_sub_f32_e32 v237, 0, v114
	v_sub_f32_e32 v238, 0, v114
	v_sub_f32_e32 v239, 0, v114
	v_sub_f32_e32 v240, 0, v114
	v_sub_f32_e32 v241, 0, v114
	v_sub_f32_e32 v242, 0, v114
	v_sub_f32_e32 v243, 0, v114
	v_lshlrev_b32_e32 v140, 4, v8
	v_or_b32_e32 v147, 1, v128
	v_lshl_add_u64 v[116:117], v[0:1], 0, v[4:5]
	v_lshl_add_u64 v[118:119], v[0:1], 0, v[14:15]
	s_mov_b32 s22, 0
	v_lshl_add_u64 v[120:121], v[136:137], 0, v[2:3]
	v_lshl_add_u64 v[122:123], v[136:137], 0, v[6:7]
	v_lshl_add_u64 v[124:125], v[136:137], 0, v[10:11]
	s_mov_b64 s[44:45], 0
	v_mov_b32_e32 v0, 0
	v_mov_b32_e32 v1, v126
	v_mov_b32_e32 v2, v126
	v_mov_b32_e32 v3, v126
	v_mov_b32_e32 v4, v126
	v_mov_b32_e32 v5, v126
	v_mov_b32_e32 v6, v126
	v_mov_b32_e32 v7, v126
	v_mov_b32_e32 v8, v126
	v_mov_b32_e32 v9, v126
	v_mov_b32_e32 v10, v126
	v_mov_b32_e32 v11, v126
	v_mov_b32_e32 v12, v126
	v_mov_b32_e32 v13, v126
	v_mov_b32_e32 v14, v126
	v_mov_b32_e32 v15, v126
	v_mov_b32_e32 v16, v126
	v_mov_b32_e32 v17, v126
	v_mov_b32_e32 v18, v126
	v_mov_b32_e32 v19, v126
	v_mov_b32_e32 v20, v126
	v_mov_b32_e32 v21, v126
	v_mov_b32_e32 v22, v126
	v_mov_b32_e32 v23, v126
	v_mov_b32_e32 v24, v126
	v_mov_b32_e32 v25, v126
	v_mov_b32_e32 v26, v126
	v_mov_b32_e32 v27, v126
	v_mov_b32_e32 v28, v126
	v_mov_b32_e32 v29, v126
	v_mov_b32_e32 v30, v126
	v_mov_b32_e32 v31, v126
	s_waitcnt vmcnt(0) lgkmcnt(0)
	s_barrier
	v_readfirstlane_b32 s32, v132
	v_readfirstlane_b32 s73, v135
	s_mov_b64 s[36:37], s[74:75]
	s_mov_b64 s[38:39], s[74:75]
	s_branch .LBB0_87

; template <int DQK, bool MIXA, bool PIPE>
; DI void attn_item(const Params& P, int layer, char* smem, int b, int h, int qt) {
;     ...
;       for (int s = 0; s < NS; ++s) sacc[0] = __builtin_amdgcn_mfma_f32_32x32x16_bf16(kf[0][s], qf[s], sacc[0], 0, 0, 0);
;       bf16x8 vf[2][2][2];
; #pragma unroll
;       for (int d = 0; d < 2; ++d)
; #pragma unroll
;         for (int kb = 0; kb < 2; ++kb)
; #pragma unroll
;           for (int s2 = 0; s2 < 2; ++s2)
;             vf[d][kb][s2] = *(const bf16x8*)(Vs + (d * 32 + l31) * 128 + (((4 * kb + 2 * s2 + H) ^ swv) << 4));
;       __builtin_amdgcn_sched_barrier(0);
;       const bool near = MIXA && (kc >= cw - 2);
;       f32x2 ls2 = {0.f, 0.f};
;       const f32x2 sl2v = {sl2, sl2}, mfixv = {mfix, mfix};
;       unsigned pkw[2][2][4];
;       unsigned mrot[2];
; #pragma unroll
;       for (int kb = 0; kb < 2; ++kb) mrot[kb] = MIXA ? ((mw[kb] >> (8 * H)) << 8) : 0u;
;       auto chunk = [&](int kb, int c) __attribute__((always_inline)) {
;         const int s2 = 1 - (c >> 2), e = 3 - (c & 3);
;         const int r0 = 8 * s2 + 2 * e;
;         if (MIXA && c == 4) mrot[kb] <<= 8;
;         f32x2 xv2 = {sacc[kb][r0], sacc[kb][r0 + 1]};
;         xv2 = xv2 * sl2v - mfixv;
;         if (MIXA) {
;           if (near) {
;             const int kl = 16 * (r0 >> 3) + 8 * H + (r0 & 7);
;             const int rel = kc * 64 + 32 * kb + kl - qpos;
;             xv2.x += biasT[rel + 192];
;             xv2.y += biasT[rel + 193];
;           }
;         }
;         f32x2 p2 = {__builtin_amdgcn_exp2f(xv2.x), __builtin_amdgcn_exp2f(xv2.y)};
;         if (MIXA) {
;           float px = p2.x, py = p2.y;
;           asm volatile("v_add_co_u32 %0, vcc, %0, %0\n\tv_cndmask_b32 %1, 0, %1, vcc" : "+v"(mrot[kb]), "+v"(py) : : "vcc");
;           asm volatile("v_add_co_u32 %0, vcc, %0, %0\n\tv_cndmask_b32 %1, 0, %1, vcc" : "+v"(mrot[kb]), "+v"(px) : : "vcc");
;           p2.x = px; p2.y = py;
;         }
;         ls2 += p2;
;         pkw[kb][s2][e] = pk2(p2.x, p2.y);
;       };
;       {
;         int c0 = 0;
; #pragma unroll
;         for (int s = 0; s < NS; ++s) {
;           sacc[1] = __builtin_amdgcn_mfma_f32_32x32x16_bf16(kf[1][s], qf[s], sacc[1], 0, 0, 0);
;           const int cend = (8 * (s + 1)) / NS;
; #pragma unroll
;           for (int c = 0; c < 8; ++c) if (c >= c0 && c < cend) chunk(0, c);
;           c0 = cend;
.LBB0_87:
	s_add_i32 s20, s22, 1
	s_bitcmp1_b32 s20, 0
	s_cselect_b32 s21, 0x5000, 0
	s_add_u32 m0, s21, s32
	s_add_u32 s18, s21, s73
	global_load_lds_dwordx4 v120, s[36:37]
	s_add_u32 m0, m0, 0x400
	s_nop 0
	global_load_lds_dwordx4 v122, s[36:37]
	s_add_u32 m0, m0, 0x400
	s_nop 0
	global_load_lds_dwordx4 v124, s[36:37]
	s_add_u32 m0, s18, 0x3000
	v_cmp_le_i32_e32 vcc, s22, v127
	global_load_lds_dwordx4 v116, s[38:39]
	s_add_u32 m0, s18, 0x3400
	s_nop 0
	global_load_lds_dwordx4 v118, s[38:39]
	s_and_saveexec_b64 s[18:19], vcc
	s_cbranch_execz .LBB0_86
	s_bitcmp1_b32 s22, 0
	s_cselect_b32 s22, 0x5000, 0
	v_add_u32_e32 v32, s22, v141
	v_add_u32_e32 v36, v32, v140
	v_add_u32_e32 v44, v32, v142
	v_add_u32_e32 v48, v32, v143
	v_add_u32_e32 v49, v32, v144
	v_add_u32_e32 v50, v32, v145
	v_add_u32_e32 v51, v32, v146
	ds_read_b128 v[32:35], v36
	ds_read_b128 v[36:39], v36 offset:6144
	ds_read_b128 v[40:43], v44
	ds_read_b128 v[148:151], v44 offset:6144
	ds_read_b128 v[44:47], v48
	ds_read_b128 v[152:155], v48 offset:6144
	ds_read_b128 v[88:91], v49
	ds_read_b128 v[156:159], v49 offset:6144
	ds_read_b128 v[92:95], v50
	ds_read_b128 v[208:211], v50 offset:6144
	ds_read_b128 v[96:99], v51
	ds_read_b128 v[212:215], v51 offset:6144
	s_waitcnt lgkmcnt(0)
	v_mfma_f32_32x32x16_bf16 v[48:63], v[32:35], v[84:87], v[228:243]
	v_or_b32_e32 v32, s22, v129
	v_add_u32_e32 v33, v32, v134
	v_add_u32_e32 v34, v32, v133
	v_add_u32_e32 v35, v32, v130
	v_add_u32_e32 v32, v32, v131
	ds_read_b128 v[216:219], v33 offset:12288
	ds_read_b128 v[108:111], v34 offset:12288
	v_mfma_f32_32x32x16_bf16 v[48:63], v[40:43], v[80:83], v[48:63]
	v_mfma_f32_32x32x16_bf16 v[48:63], v[44:47], v[76:79], v[48:63]
	v_mfma_f32_32x32x16_bf16 v[48:63], v[88:91], v[72:75], v[48:63]
	ds_read_b128 v[88:91], v35 offset:12288
	v_mfma_f32_32x32x16_bf16 v[48:63], v[92:95], v[68:71], v[48:63]
	v_mfma_f32_32x32x16_bf16 v[48:63], v[96:99], v[64:67], v[48:63]
	ds_read_b128 v[92:95], v32 offset:12288
	ds_read_b128 v[220:223], v33 offset:16384
	ds_read_b128 v[104:107], v34 offset:16384
	ds_read_b128 v[100:103], v35 offset:16384
	ds_read_b128 v[96:99], v32 offset:16384
	s_nop 6
	s_nop 0
	v_exp_f32_e32 v32, v62
	v_exp_f32_e32 v33, v63
	s_nop 0
	v_pk_add_f32 v[224:225], v[32:33], 0 op_sel_hi:[1,0]
	v_cvt_pk_bf16_f32 v63, v32, v33
	v_mfma_f32_32x32x16_bf16 v[32:47], v[36:39], v[84:87], v[228:243]
	v_mfma_f32_32x32x16_bf16 v[32:47], v[148:151], v[80:83], v[32:47]
	v_exp_f32_e32 v60, v60
	v_exp_f32_e32 v61, v61
	s_nop 0
	v_pk_add_f32 v[224:225], v[60:61], v[224:225]
	v_cvt_pk_bf16_f32 v62, v60, v61
	v_exp_f32_e32 v58, v58
	v_exp_f32_e32 v59, v59
	v_exp_f32_e32 v56, v56
	v_exp_f32_e32 v57, v57
	v_mfma_f32_32x32x16_bf16 v[32:47], v[152:155], v[76:79], v[32:47]
	v_add_f32_e64 v148, v58, v224
	v_add_f32_e64 v149, v59, v225
	v_cvt_pk_bf16_f32 v61, v58, v59
	v_add_f32_e64 v58, v56, v148
	v_add_f32_e64 v59, v57, v149
	v_cvt_pk_bf16_f32 v60, v56, v57
	v_mfma_f32_32x32x16_bf16 v[32:47], v[156:159], v[72:75], v[32:47]
	v_exp_f32_e32 v54, v54
	v_exp_f32_e32 v55, v55
	s_nop 0
	v_pk_add_f32 v[56:57], v[54:55], v[58:59]
	v_cvt_pk_bf16_f32 v55, v54, v55
	v_mfma_f32_32x32x16_bf16 v[32:47], v[208:211], v[68:71], v[32:47]
	v_exp_f32_e32 v52, v52
	v_exp_f32_e32 v53, v53
	s_nop 0
	v_pk_add_f32 v[56:57], v[52:53], v[56:57]
	v_cvt_pk_bf16_f32 v54, v52, v53
	v_exp_f32_e32 v50, v50
	v_exp_f32_e32 v51, v51
	v_exp_f32_e32 v48, v48
	v_exp_f32_e32 v49, v49
	v_mfma_f32_32x32x16_bf16 v[32:47], v[212:215], v[64:67], v[32:47]
	v_add_f32_e64 v56, v50, v56
	v_add_f32_e64 v57, v51, v57
	v_cvt_pk_bf16_f32 v53, v50, v51
	v_cvt_pk_bf16_f32 v52, v48, v49
	v_add_f32_e64 v48, v48, v56
	v_add_f32_e64 v49, v49, v57
	s_waitcnt lgkmcnt(0)
	v_mfma_f32_32x32x16_bf16 v[0:15], v[216:219], v[52:55], v[0:15]
	s_nop 3
	v_exp_f32_e32 v46, v46
	v_exp_f32_e32 v47, v47
	v_exp_f32_e32 v44, v44
	v_exp_f32_e32 v45, v45
	v_pk_add_f32 v[48:49], v[48:49], v[46:47]
	v_cvt_pk_bf16_f32 v47, v46, v47
	v_pk_add_f32 v[48:49], v[44:45], v[48:49]
	v_cvt_pk_bf16_f32 v46, v44, v45
	v_mfma_f32_32x32x16_bf16 v[16:31], v[220:223], v[52:55], v[16:31]
	v_exp_f32_e32 v42, v42
	v_exp_f32_e32 v43, v43
	v_exp_f32_e32 v40, v40
	v_exp_f32_e32 v41, v41
	v_pk_add_f32 v[48:49], v[42:43], v[48:49]
	v_cvt_pk_bf16_f32 v45, v42, v43
	v_pk_add_f32 v[42:43], v[40:41], v[48:49]
	v_cvt_pk_bf16_f32 v44, v40, v41
	v_mfma_f32_32x32x16_bf16 v[0:15], v[108:111], v[60:63], v[0:15]
	v_exp_f32_e32 v38, v38
	v_exp_f32_e32 v39, v39
	v_exp_f32_e32 v36, v36
	v_exp_f32_e32 v37, v37
	v_pk_add_f32 v[40:41], v[38:39], v[42:43]
	v_cvt_pk_bf16_f32 v39, v38, v39
	v_pk_add_f32 v[40:41], v[36:37], v[40:41]
	v_cvt_pk_bf16_f32 v38, v36, v37
	v_mfma_f32_32x32x16_bf16 v[16:31], v[104:107], v[60:63], v[16:31]
	v_exp_f32_e32 v34, v34
	v_exp_f32_e32 v35, v35
	v_exp_f32_e32 v32, v32
	v_exp_f32_e32 v33, v33
	v_cvt_pk_bf16_f32 v37, v34, v35
	v_cvt_pk_bf16_f32 v36, v32, v33
	s_nop 1
	v_mfma_f32_32x32x16_bf16 v[0:15], v[88:91], v[36:39], v[0:15]
	v_add_f32_e64 v34, v34, v40
	v_add_f32_e64 v35, v35, v41
	v_add_f32_e64 v32, v32, v34
	v_add_f32_e64 v33, v33, v35
	v_add_f32_e32 v32, v32, v33
	v_add_f32_e32 v126, v126, v32
	v_mfma_f32_32x32x16_bf16 v[16:31], v[100:103], v[36:39], v[16:31]
	v_mfma_f32_32x32x16_bf16 v[0:15], v[92:95], v[44:47], v[0:15]
	v_mfma_f32_32x32x16_bf16 v[16:31], v[96:99], v[44:47], v[16:31]
	s_branch .LBB0_86
; template <int DQK, bool MIXA, bool PIPE>
; DI void attn_item(const Params& P, int layer, char* smem, int b, int h, int qt) {
;     ...
;       for (int s = 0; s < NS; ++s) sacc[0] = __builtin_amdgcn_mfma_f32_32x32x16_bf16(kf[0][s], qf[s], sacc[0], 0, 0, 0);
;       bf16x8 vf[2][2][2];
; #pragma unroll
;       for (int d = 0; d < 2; ++d)
; #pragma unroll
;         for (int kb = 0; kb < 2; ++kb)
; #pragma unroll
;           for (int s2 = 0; s2 < 2; ++s2)
;             vf[d][kb][s2] = *(const bf16x8*)(Vs + (d * 32 + l31) * 128 + (((4 * kb + 2 * s2 + H) ^ swv) << 4));
;       __builtin_amdgcn_sched_barrier(0);
;       const bool near = MIXA && (kc >= cw - 2);
;       f32x2 ls2 = {0.f, 0.f};
;       const f32x2 sl2v = {sl2, sl2}, mfixv = {mfix, mfix};
;       unsigned pkw[2][2][4];
;       unsigned mrot[2];
; #pragma unroll
;       for (int kb = 0; kb < 2; ++kb) mrot[kb] = MIXA ? ((mw[kb] >> (8 * H)) << 8) : 0u;
;       auto chunk = [&](int kb, int c) __attribute__((always_inline)) {
;         const int s2 = 1 - (c >> 2), e = 3 - (c & 3);
;         const int r0 = 8 * s2 + 2 * e;
;         if (MIXA && c == 4) mrot[kb] <<= 8;
;         f32x2 xv2 = {sacc[kb][r0], sacc[kb][r0 + 1]};
;         xv2 = xv2 * sl2v - mfixv;
;         if (MIXA) {
;           if (near) {
;             const int kl = 16 * (r0 >> 3) + 8 * H + (r0 & 7);
;             const int rel = kc * 64 + 32 * kb + kl - qpos;
;             xv2.x += biasT[rel + 192];
;             xv2.y += biasT[rel + 193];
;           }
;         }
;         f32x2 p2 = {__builtin_amdgcn_exp2f(xv2.x), __builtin_amdgcn_exp2f(xv2.y)};
;         if (MIXA) {
;           float px = p2.x, py = p2.y;
;           asm volatile("v_add_co_u32 %0, vcc, %0, %0\n\tv_cndmask_b32 %1, 0, %1, vcc" : "+v"(mrot[kb]), "+v"(py) : : "vcc");
;           asm volatile("v_add_co_u32 %0, vcc, %0, %0\n\tv_cndmask_b32 %1, 0, %1, vcc" : "+v"(mrot[kb]), "+v"(px) : : "vcc");
;           p2.x = px; p2.y = py;
;         }
;         ls2 += p2;
;         pkw[kb][s2][e] = pk2(p2.x, p2.y);
;       };
;       {
;         int c0 = 0;
; #pragma unroll
;         for (int s = 0; s < NS; ++s) {
;           sacc[1] = __builtin_amdgcn_mfma_f32_32x32x16_bf16(kf[1][s], qf[s], sacc[1], 0, 0, 0);
;           const int cend = (8 * (s + 1)) / NS;
; #pragma unroll
;           for (int c = 0; c < 8; ++c) if (c >= c0 && c < cend) chunk(0, c);
;           c0 = cend;
.LBB0_89:
	s_or_b64 exec, exec, s[44:45]
	v_cmp_lt_i32_e32 vcc, v128, v127
	s_and_saveexec_b64 s[18:19], vcc
	s_cbranch_execz .LBB0_91
	v_add_u32_e32 v33, v32, v141
	v_add_u32_e32 v38, v33, v140
	v_add_u32_e32 v46, v33, v142
	v_add_u32_e32 v47, v33, v143
	v_add_u32_e32 v48, v33, v144
	v_add_u32_e32 v49, v33, v145
	v_add_u32_e32 v33, v33, v146
	ds_read_b128 v[34:37], v38
	ds_read_b128 v[38:41], v38 offset:6144
	ds_read_b128 v[42:45], v46
	ds_read_b128 v[116:119], v46 offset:6144
	ds_read_b128 v[88:91], v47
	ds_read_b128 v[120:123], v47 offset:6144
	ds_read_b128 v[92:95], v48
	ds_read_b128 v[140:143], v48 offset:6144
	ds_read_b128 v[96:99], v49
	ds_read_b128 v[144:147], v49 offset:6144
	ds_read_b128 v[100:103], v33
	ds_read_b128 v[148:151], v33 offset:6144
	s_waitcnt lgkmcnt(11)
	v_mfma_f32_32x32x16_bf16 v[48:63], v[34:37], v[84:87], v[228:243]
	v_add_u32_e32 v32, v32, v129
	v_add_u32_e32 v33, v32, v134
	v_add_u32_e32 v34, v32, v133
	v_add_u32_e32 v35, v32, v130
	v_add_u32_e32 v32, v32, v131
	ds_read_b128 v[152:155], v33 offset:12288
	ds_read_b128 v[108:111], v34 offset:12288
	s_waitcnt lgkmcnt(11)
	v_mfma_f32_32x32x16_bf16 v[48:63], v[42:45], v[80:83], v[48:63]
	s_waitcnt lgkmcnt(9)
	v_mfma_f32_32x32x16_bf16 v[48:63], v[88:91], v[76:79], v[48:63]
	ds_read_b128 v[88:91], v35 offset:12288
	s_waitcnt lgkmcnt(8)
	v_mfma_f32_32x32x16_bf16 v[48:63], v[92:95], v[72:75], v[48:63]
	s_waitcnt lgkmcnt(6)
	v_mfma_f32_32x32x16_bf16 v[48:63], v[96:99], v[68:71], v[48:63]
	s_waitcnt lgkmcnt(4)
	v_mfma_f32_32x32x16_bf16 v[48:63], v[100:103], v[64:67], v[48:63]
	ds_read_b128 v[92:95], v32 offset:12288
	ds_read_b128 v[128:131], v33 offset:16384
	ds_read_b128 v[104:107], v34 offset:16384
	ds_read_b128 v[100:103], v35 offset:16384
	ds_read_b128 v[96:99], v32 offset:16384
	s_nop 6
	s_nop 0
	v_exp_f32_e32 v32, v62
	v_exp_f32_e32 v33, v63
	s_nop 0
	v_pk_add_f32 v[124:125], v[32:33], 0 op_sel_hi:[1,0]
	v_cvt_pk_bf16_f32 v63, v32, v33
	v_mfma_f32_32x32x16_bf16 v[32:47], v[38:41], v[84:87], v[228:243]
	v_mfma_f32_32x32x16_bf16 v[32:47], v[116:119], v[80:83], v[32:47]
	v_exp_f32_e32 v60, v60
	v_exp_f32_e32 v61, v61
	s_nop 0
	v_pk_add_f32 v[84:85], v[60:61], v[124:125]
	v_cvt_pk_bf16_f32 v62, v60, v61
	v_exp_f32_e32 v58, v58
	v_exp_f32_e32 v59, v59
	v_exp_f32_e32 v56, v56
	v_exp_f32_e32 v57, v57
	v_mfma_f32_32x32x16_bf16 v[32:47], v[120:123], v[76:79], v[32:47]
	v_add_f32_e64 v80, v58, v84
	v_add_f32_e64 v81, v59, v85
	v_cvt_pk_bf16_f32 v61, v58, v59
	v_add_f32_e64 v58, v56, v80
	v_add_f32_e64 v59, v57, v81
	v_cvt_pk_bf16_f32 v60, v56, v57
	v_mfma_f32_32x32x16_bf16 v[32:47], v[140:143], v[72:75], v[32:47]
	v_exp_f32_e32 v54, v54
	v_exp_f32_e32 v55, v55
	s_nop 0
	v_pk_add_f32 v[56:57], v[54:55], v[58:59]
	v_cvt_pk_bf16_f32 v55, v54, v55
	v_mfma_f32_32x32x16_bf16 v[32:47], v[144:147], v[68:71], v[32:47]
	v_exp_f32_e32 v52, v52
	v_exp_f32_e32 v53, v53
	s_nop 0
	v_pk_add_f32 v[56:57], v[52:53], v[56:57]
	v_cvt_pk_bf16_f32 v54, v52, v53
	v_exp_f32_e32 v50, v50
	v_exp_f32_e32 v51, v51
	v_exp_f32_e32 v48, v48
	v_exp_f32_e32 v49, v49
	s_waitcnt lgkmcnt(8)
	v_mfma_f32_32x32x16_bf16 v[32:47], v[148:151], v[64:67], v[32:47]
	v_add_f32_e64 v56, v50, v56
	v_add_f32_e64 v57, v51, v57
	v_cvt_pk_bf16_f32 v53, v50, v51
	v_cvt_pk_bf16_f32 v52, v48, v49
	v_add_f32_e64 v48, v48, v56
	v_add_f32_e64 v49, v49, v57
	s_waitcnt lgkmcnt(7)
	v_mfma_f32_32x32x16_bf16 v[0:15], v[152:155], v[52:55], v[0:15]
	s_nop 3
	v_exp_f32_e32 v46, v46
	v_exp_f32_e32 v47, v47
	v_exp_f32_e32 v44, v44
	v_exp_f32_e32 v45, v45
	v_pk_add_f32 v[48:49], v[48:49], v[46:47]
	v_cvt_pk_bf16_f32 v47, v46, v47
	v_pk_add_f32 v[48:49], v[44:45], v[48:49]
	v_cvt_pk_bf16_f32 v46, v44, v45
	s_waitcnt lgkmcnt(3)
	v_mfma_f32_32x32x16_bf16 v[16:31], v[128:131], v[52:55], v[16:31]
	v_exp_f32_e32 v42, v42
	v_exp_f32_e32 v43, v43
	v_exp_f32_e32 v40, v40
	v_exp_f32_e32 v41, v41
	v_pk_add_f32 v[48:49], v[42:43], v[48:49]
	v_cvt_pk_bf16_f32 v45, v42, v43
	v_pk_add_f32 v[42:43], v[40:41], v[48:49]
	v_cvt_pk_bf16_f32 v44, v40, v41
	v_mfma_f32_32x32x16_bf16 v[0:15], v[108:111], v[60:63], v[0:15]
	v_exp_f32_e32 v38, v38
	v_exp_f32_e32 v39, v39
	v_exp_f32_e32 v36, v36
	v_exp_f32_e32 v37, v37
	v_pk_add_f32 v[40:41], v[38:39], v[42:43]
	v_cvt_pk_bf16_f32 v39, v38, v39
	v_pk_add_f32 v[40:41], v[36:37], v[40:41]
	v_cvt_pk_bf16_f32 v38, v36, v37
	s_waitcnt lgkmcnt(2)
	v_mfma_f32_32x32x16_bf16 v[16:31], v[104:107], v[60:63], v[16:31]
	v_exp_f32_e32 v34, v34
	v_exp_f32_e32 v35, v35
	v_exp_f32_e32 v32, v32
	v_exp_f32_e32 v33, v33
	v_cvt_pk_bf16_f32 v37, v34, v35
	v_cvt_pk_bf16_f32 v36, v32, v33
	s_nop 1
	v_mfma_f32_32x32x16_bf16 v[0:15], v[88:91], v[36:39], v[0:15]
	v_add_f32_e64 v34, v34, v40
	v_add_f32_e64 v35, v35, v41
	v_add_f32_e64 v32, v32, v34
	v_add_f32_e64 v33, v33, v35
	v_add_f32_e32 v32, v32, v33
	v_add_f32_e32 v126, v126, v32
	s_waitcnt lgkmcnt(1)
	v_mfma_f32_32x32x16_bf16 v[16:31], v[100:103], v[36:39], v[16:31]
	v_mfma_f32_32x32x16_bf16 v[0:15], v[92:95], v[44:47], v[0:15]
	s_waitcnt lgkmcnt(0)
	v_mfma_f32_32x32x16_bf16 v[16:31], v[96:99], v[44:47], v[16:31]

; template <int DQK, bool MIXA, bool PIPE>
; DI void attn_item(const Params& P, int layer, char* smem, int b, int h, int qt) {
;     ...
;     if (MIXA) {
;       const float b15 = P.rel_bias[15 * 8 + h];
;       float bm = 0.f;
;       for (int i = 0; i < 32; ++i) bm = fmaxf(bm, P.rel_bias[i * 8 + h] - b15);
;       mfix += bm * LOG2E;
;     }
;   }
;   if (MIXA) {
;     const int rel = tid - 192;
;     const float b15 = P.rel_bias[15 * 8 + h];
;     biasT[tid] = (P.rel_bias[t5_bucket(rel) * 8 + h] - b15) * LOG2E;
;   }
;   bf16x8 qf[NS];
; #pragma unroll
;   for (int s = 0; s < NS; ++s) qf[s] = *(const bf16x8*)(Qp + tokq * ldq + 16 * s + 8 * H);
;   const int nkt = 2 * qt + 2;
;   unsigned koff[NKI], voff[2];
; #pragma unroll
;   for (int i = 0; i < NKI; ++i) {
;     const int e = (w * NKI + i) * 64 + lane;
;     const int row = e / KCH, slot = e % KCH;
;     const int c = slot ^ (MIXA ? ((row >> 1) & 7) : ((row >> 2) & 3));
;     koff[i] = (unsigned)((row * ldk + c * 8) * 2);
;   }
; #pragma unroll
;   for (int i = 0; i < 2; ++i) {
;     const int e = (w * 2 + i) * 64 + lane;
;     const int row = e >> 3, slot = e & 7;
;     const int c = slot ^ ((row >> 1) & 7);
;     voff[i] = (unsigned)((row * S_ + c * 8) * 2);
;   }
;   unsigned mwn[2] = {0u, 0u};
;   auto issue_loads = [&](int kt) __attribute__((always_inline)) {
;     const char* kbp = (const char*)(Kp + (size_t)(kt * 64) * ldk);
;     const char* vbp = (const char*)(VT + kt * 64);
;     char* sk = smem + (kt & 1) * STG_B;
; #pragma unroll
;     for (int i = 0; i < NKI; ++i)
;       __builtin_amdgcn_global_load_lds((const unsigned*)(kbp + koff[i]), (unsigned*)(sk + (w * NKI + i) * 1024), 16, 0, 0);
; #pragma unroll
;     for (int i = 0; i < 2; ++i)
;       __builtin_amdgcn_global_load_lds((const unsigned*)(vbp + voff[i]), (unsigned*)(sk + KTILE_B + (w * 2 + i) * 1024), 16, 0, 0);
;     if (MIXA) {
;       if (kt <= cw) {
;         const unsigned* mp = mask + mask_base(b, cw) + (2 * kt) * 64 + (qpos & 63);
;         mwn[0] = mp[0]; mwn[1] = mp[64];
;       }
;     }
;   };
;   issue_loads(0);
;   f32x16 o[2];
; #pragma unroll
;   for (int d = 0; d < 2; ++d)
; #pragma unroll
;     for (int i = 0; i < 16; ++i) o[d][i] = 0.f;
;   float l = 0.f;
;   const int pr = (l31 & ~12) | ((l31 & 4) << 1) | ((l31 & 8) >> 1);
;   const int swk = MIXA ? ((pr >> 1) & 7) : ((pr >> 2) & 3), swv = (l31 >> 1) & 7;
.LBB0_107:
	s_or_b64 exec, exec, s[18:19]
	v_mad_u64_u32 v[126:127], s[18:19], v0, s33, 0
	v_mul_f32_e32 v0, 0x42828f5c, v12
	v_mad_i32_i24 v127, v1, s33, v127
	v_mul_f32_e32 v0, v11, v0
	v_sub_f32_e32 v1, v47, v13
	v_sub_f32_e32 v11, v48, v13
	v_max3_f32 v1, v1, 0, v11
	v_sub_f32_e32 v11, v44, v13
	v_sub_f32_e32 v12, v45, v13
	v_max3_f32 v1, v1, v11, v12
	v_sub_f32_e32 v11, v42, v13
	v_sub_f32_e32 v12, v43, v13
	v_max3_f32 v1, v1, v11, v12
	v_sub_f32_e32 v11, v38, v13
	v_sub_f32_e32 v12, v39, v13
	v_max3_f32 v1, v1, v11, v12
	v_sub_f32_e32 v11, v40, v13
	v_sub_f32_e32 v12, v41, v13
	v_max3_f32 v1, v1, v11, v12
	v_sub_f32_e32 v11, v36, v13
	v_sub_f32_e32 v12, v37, v13
	v_max3_f32 v1, v1, v11, v12
	v_sub_f32_e32 v11, v32, v13
	v_sub_f32_e32 v12, v33, v13
	v_max3_f32 v1, v1, v11, v12
	v_sub_f32_e32 v11, v31, v13
	v_sub_f32_e32 v12, v13, v13
	v_max3_f32 v1, v1, v11, v12
	v_sub_f32_e32 v11, v28, v13
	v_sub_f32_e32 v12, v29, v13
	v_max3_f32 v1, v1, v11, v12
	v_sub_f32_e32 v11, v26, v13
	v_sub_f32_e32 v12, v27, v13
	v_max3_f32 v1, v1, v11, v12
	v_sub_f32_e32 v11, v24, v13
	v_sub_f32_e32 v12, v25, v13
	v_max3_f32 v1, v1, v11, v12
	v_sub_f32_e32 v11, v22, v13
	v_sub_f32_e32 v12, v23, v13
	v_max3_f32 v1, v1, v11, v12
	v_sub_f32_e32 v11, v20, v13
	v_sub_f32_e32 v12, v21, v13
	v_max3_f32 v1, v1, v11, v12
	v_sub_f32_e32 v11, v18, v13
	v_sub_f32_e32 v12, v19, v13
	v_max3_f32 v1, v1, v11, v12
	v_sub_f32_e32 v11, v16, v13
	v_sub_f32_e32 v12, v17, v13
	v_max3_f32 v1, v1, v11, v12
	v_sub_f32_e32 v11, v14, v13
	v_sub_f32_e32 v12, v15, v13
	v_max3_f32 v1, v1, v11, v12
	v_mul_f32_e32 v128, 0x3fb8aa3b, v1
	v_lshlrev_b32_e32 v1, 1, v10
	v_lshrrev_b32_e32 v11, 1, v10
	v_fmac_f32_e32 v128, 0x3e38aa3b, v0
	v_and_b32_e32 v0, 19, v10
	v_and_b32_e32 v1, 8, v1
	v_and_b32_e32 v12, 4, v11
	v_or3_b32 v0, v1, v0, v12
	v_lshrrev_b32_e32 v1, 1, v0
	v_lshlrev_b32_e32 v155, 7, v0
	v_bitop3_b32 v0, v1, v139, 7 bitop3:0x6c
	v_lshlrev_b32_e32 v157, 4, v0
	v_or_b32_e32 v0, 2, v139
	v_bitop3_b32 v0, v1, v0, 7 bitop3:0x6c
	v_lshlrev_b32_e32 v158, 4, v0
	v_or_b32_e32 v0, 4, v139
	v_bitop3_b32 v0, v1, v0, 7 bitop3:0x6c
	v_lshlrev_b32_e32 v159, 4, v0
	v_or_b32_e32 v0, 6, v139
	v_bfe_u32 v10, v10, 1, 3
	v_bitop3_b32 v0, v1, v0, 7 bitop3:0x6c
	v_lshlrev_b32_e32 v160, 4, v0
	v_bitop3_b32 v0, v139, v10, 4 bitop3:0x36
	v_lshlrev_b32_e32 v151, 4, v0
	v_bitop3_b32 v0, v139, v11, 7 bitop3:0x78
	v_lshlrev_b32_e32 v154, 4, v0
	v_bitop3_b32 v0, v139, v10, 2 bitop3:0x36
	v_lshlrev_b32_e32 v153, 4, v0
	v_bitop3_b32 v0, v139, v10, 6 bitop3:0x36
	v_lshlrev_b32_e32 v152, 4, v0
	v_lshlrev_b32_e32 v0, 5, v139
	v_add_lshl_u32 v1, v50, v51, 2
	v_sub_u32_e32 v0, v0, v1
	v_add_u32_e32 v162, 0xa300, v0
	v_lshlrev_b64 v[0:1], 2, v[6:7]
	v_lshlrev_b32_e32 v6, 12, v49
	v_lshl_add_u64 v[130:131], v[8:9], 2, v[0:1]
	v_add_u32_e32 v0, s86, v46
	v_mov_b32_e32 v1, v137
	s_mov_b64 s[18:19], 0x1b000080
	v_lshl_or_b32 v6, v30, 19, v6
	v_lshl_add_u64 v[0:1], v[0:1], 0, s[18:19]
	v_and_or_b32 v6, v6, s25, v54
	v_mov_b32_e32 v7, v137
	v_lshl_add_u64 v[132:133], v[0:1], 0, v[6:7]
	v_add_u32_e32 v6, v52, v49
	v_mov_b32_e32 v7, 0x40000
	v_lshl_add_u32 v6, v6, 12, v7
	s_movk_i32 s0, 0x8000
	v_and_or_b32 v6, v6, s0, v53
	v_readlane_b32 s0, v253, 17
	s_waitcnt vmcnt(0)
	v_mov_b32_e32 v7, v137
	v_readlane_b32 s1, v253, 18
	v_mov_b32_e32 v125, 0
	v_lshl_add_u64 v[134:135], v[0:1], 0, v[6:7]
	v_lshl_add_u64 v[0:1], s[0:1], 0, v[136:137]
	v_lshlrev_b32_e32 v147, 3, v139
	v_lshlrev_b32_e32 v150, 7, v51
	v_add_u32_e32 v148, -2, v145
	v_mov_b32_e32 v129, v128
	v_sub_f32_e32 v228, 0, v128
	v_sub_f32_e32 v229, 0, v128
	v_sub_f32_e32 v230, 0, v128
	v_sub_f32_e32 v231, 0, v128
	v_sub_f32_e32 v232, 0, v128
	v_sub_f32_e32 v233, 0, v128
	v_sub_f32_e32 v234, 0, v128
	v_sub_f32_e32 v235, 0, v128
	v_sub_f32_e32 v236, 0, v128
	v_sub_f32_e32 v237, 0, v128
	v_sub_f32_e32 v238, 0, v128
	v_sub_f32_e32 v239, 0, v128
	v_sub_f32_e32 v240, 0, v128
	v_sub_f32_e32 v241, 0, v128
	v_sub_f32_e32 v242, 0, v128
	v_sub_f32_e32 v243, 0, v128
	v_lshl_or_b32 v149, v34, 1, 1
	v_lshl_add_u64 v[140:141], v[0:1], 0, v[2:3]
	v_lshl_add_u64 v[142:143], v[0:1], 0, v[4:5]
	s_mov_b32 s22, 0
	s_mov_b64 s[58:59], 0
	v_mov_b32_e32 v0, 0
	v_mov_b32_e32 v1, v125
	v_mov_b32_e32 v2, v125
	v_mov_b32_e32 v3, v125
	v_mov_b32_e32 v4, v125
	v_mov_b32_e32 v5, v125
	v_mov_b32_e32 v6, v125
	v_mov_b32_e32 v7, v125
	v_mov_b32_e32 v8, v125
	v_mov_b32_e32 v9, v125
	v_mov_b32_e32 v10, v125
	v_mov_b32_e32 v11, v125
	v_mov_b32_e32 v12, v125
	v_mov_b32_e32 v13, v125
	v_mov_b32_e32 v14, v125
	v_mov_b32_e32 v15, v125
	v_mov_b32_e32 v16, v125
	v_mov_b32_e32 v17, v125
	v_mov_b32_e32 v18, v125
	v_mov_b32_e32 v19, v125
	v_mov_b32_e32 v20, v125
	v_mov_b32_e32 v21, v125
	v_mov_b32_e32 v22, v125
	v_mov_b32_e32 v23, v125
	v_mov_b32_e32 v24, v125
	v_mov_b32_e32 v25, v125
	v_mov_b32_e32 v26, v125
	v_mov_b32_e32 v27, v125
	v_mov_b32_e32 v28, v125
	v_mov_b32_e32 v29, v125
	v_mov_b32_e32 v30, v125
	v_mov_b32_e32 v31, v125
	s_waitcnt vmcnt(0)
	v_mov_b32_e32 v136, v164
	v_mov_b32_e32 v156, v166
	s_waitcnt lgkmcnt(0)
	s_barrier
	v_readfirstlane_b32 s32, v146
	s_mov_b64 s[36:37], s[74:75]
	s_mov_b64 s[38:39], s[74:75]
	s_add_u32 s76, s74, 0x7f00000
	s_addc_u32 s77, s75, 0
	s_branch .LBB0_110

; template <int DQK, bool MIXA, bool PIPE>
; DI void attn_item(const Params& P, int layer, char* smem, int b, int h, int qt) {
;     ...
;       for (int s = 0; s < NS; ++s) sacc[0] = __builtin_amdgcn_mfma_f32_32x32x16_bf16(kf[0][s], qf[s], sacc[0], 0, 0, 0);
;       bf16x8 vf[2][2][2];
; #pragma unroll
;       for (int d = 0; d < 2; ++d)
; #pragma unroll
;         for (int kb = 0; kb < 2; ++kb)
; #pragma unroll
;           for (int s2 = 0; s2 < 2; ++s2)
;             vf[d][kb][s2] = *(const bf16x8*)(Vs + (d * 32 + l31) * 128 + (((4 * kb + 2 * s2 + H) ^ swv) << 4));
;       __builtin_amdgcn_sched_barrier(0);
;       const bool near = MIXA && (kc >= cw - 2);
;       f32x2 ls2 = {0.f, 0.f};
;       const f32x2 sl2v = {sl2, sl2}, mfixv = {mfix, mfix};
;       unsigned pkw[2][2][4];
;       unsigned mrot[2];
; #pragma unroll
;       for (int kb = 0; kb < 2; ++kb) mrot[kb] = MIXA ? ((mw[kb] >> (8 * H)) << 8) : 0u;
;       auto chunk = [&](int kb, int c) __attribute__((always_inline)) {
;         const int s2 = 1 - (c >> 2), e = 3 - (c & 3);
;         const int r0 = 8 * s2 + 2 * e;
;         if (MIXA && c == 4) mrot[kb] <<= 8;
;         f32x2 xv2 = {sacc[kb][r0], sacc[kb][r0 + 1]};
;         xv2 = xv2 * sl2v - mfixv;
;         if (MIXA) {
;           if (near) {
;             const int kl = 16 * (r0 >> 3) + 8 * H + (r0 & 7);
;             const int rel = kc * 64 + 32 * kb + kl - qpos;
;             xv2.x += biasT[rel + 192];
;             xv2.y += biasT[rel + 193];
;           }
;         }
;         f32x2 p2 = {__builtin_amdgcn_exp2f(xv2.x), __builtin_amdgcn_exp2f(xv2.y)};
;         if (MIXA) {
;           float px = p2.x, py = p2.y;
;           asm volatile("v_add_co_u32 %0, vcc, %0, %0\n\tv_cndmask_b32 %1, 0, %1, vcc" : "+v"(mrot[kb]), "+v"(py) : : "vcc");
;           asm volatile("v_add_co_u32 %0, vcc, %0, %0\n\tv_cndmask_b32 %1, 0, %1, vcc" : "+v"(mrot[kb]), "+v"(px) : : "vcc");
;           p2.x = px; p2.y = py;
;         }
;         ls2 += p2;
;         pkw[kb][s2][e] = pk2(p2.x, p2.y);
;       };
;       {
;         int c0 = 0;
; #pragma unroll
;         for (int s = 0; s < NS; ++s) {
;           sacc[1] = __builtin_amdgcn_mfma_f32_32x32x16_bf16(kf[1][s], qf[s], sacc[1], 0, 0, 0);
;           const int cend = (8 * (s + 1)) / NS;
; #pragma unroll
;           for (int c = 0; c < 8; ++c) if (c >= c0 && c < cend) chunk(0, c);
;           c0 = cend;
.LBB0_112:
	s_or_b64 exec, exec, s[18:19]
	v_cmp_le_i32_e32 vcc, s22, v145
	s_and_saveexec_b64 s[60:61], vcc
	s_cbranch_execz .LBB0_109
	s_bitcmp1_b32 s22, 0
	s_cselect_b32 s18, 0x5000, 0
	v_or_b32_e32 v32, s18, v155
	v_add_u32_e32 v33, v32, v157
	v_add_u32_e32 v44, v32, v158
	v_add_u32_e32 v48, v32, v159
	v_add_u32_e32 v49, v32, v160
	ds_read_b128 v[36:39], v33
	ds_read_b128 v[32:35], v33 offset:4096
	ds_read_b128 v[40:43], v44
	ds_read_b128 v[120:123], v44 offset:4096
	ds_read_b128 v[44:47], v48
	ds_read_b128 v[116:119], v48 offset:4096
	ds_read_b128 v[80:83], v49
	ds_read_b128 v[108:111], v49 offset:4096
	s_waitcnt lgkmcnt(0)
	v_mfma_f32_32x32x16_bf16 v[48:63], v[36:39], v[76:79], v[228:243]
	v_or_b32_e32 v36, s18, v150
	v_add_u32_e32 v37, v36, v154
	v_add_u32_e32 v38, v36, v153
	v_add_u32_e32 v39, v36, v151
	v_add_u32_e32 v36, v36, v152
	ds_read_b128 v[112:115], v37 offset:8192
	ds_read_b128 v[100:103], v38 offset:8192
	v_mfma_f32_32x32x16_bf16 v[48:63], v[40:43], v[72:75], v[48:63]
	v_mfma_f32_32x32x16_bf16 v[48:63], v[44:47], v[68:71], v[48:63]
	v_mfma_f32_32x32x16_bf16 v[48:63], v[80:83], v[64:67], v[48:63]
	ds_read_b128 v[80:83], v39 offset:8192
	ds_read_b128 v[84:87], v36 offset:8192
	ds_read_b128 v[104:107], v37 offset:12288
	ds_read_b128 v[96:99], v38 offset:12288
	ds_read_b128 v[92:95], v39 offset:12288
	ds_read_b128 v[88:91], v36 offset:12288
	v_cmp_ge_i32_e64 s[44:45], s22, v148
	s_nop 4
	s_cmp_lg_u64 s[44:45], 0
	s_cbranch_scc1 .Lmixa_near_0
.Lmixa_back_0:
	v_exp_f32_e32 v62, v62
	v_lshrrev_b32_e32 v36, v147, v166
	v_exp_f32_e32 v63, v63
	v_lshlrev_b32_e32 v166, 8, v36
	v_add_co_u32 v166, vcc, v166, v166
	v_cndmask_b32 v63, 0, v63, vcc
	v_add_co_u32 v166, vcc, v166, v166
	v_cndmask_b32 v62, 0, v62, vcc
	s_cbranch_scc1 .Lmixa_near_1
.Lmixa_back_1:
	v_exp_f32_e32 v61, v61
	v_exp_f32_e32 v60, v60
	v_mfma_f32_32x32x16_bf16 v[32:47], v[32:35], v[76:79], v[228:243]
	v_add_co_u32 v166, vcc, v166, v166
	v_cndmask_b32 v61, 0, v61, vcc
	s_nop 0
	v_add_co_u32 v166, vcc, v166, v166
	v_cndmask_b32 v60, 0, v60, vcc
	s_cbranch_scc1 .Lmixa_near_2
.Lmixa_back_2:
	v_exp_f32_e32 v59, v59
	v_exp_f32_e32 v58, v58
	v_add_co_u32 v166, vcc, v166, v166
	v_cndmask_b32 v59, 0, v59, vcc
	v_add_co_u32 v166, vcc, v166, v166
	v_cndmask_b32 v58, 0, v58, vcc
	s_cbranch_scc1 .Lmixa_near_3
.Lmixa_back_3:
	v_mfma_f32_32x32x16_bf16 v[32:47], v[120:123], v[72:75], v[32:47]
	v_exp_f32_e32 v57, v57
	v_exp_f32_e32 v56, v56
	v_add_co_u32 v166, vcc, v166, v166
	v_cndmask_b32 v57, 0, v57, vcc
	s_nop 0
	v_add_co_u32 v166, vcc, v166, v166
	v_cndmask_b32 v56, 0, v56, vcc
	s_cbranch_scc1 .Lmixa_near_4
.Lmixa_back_4:
	v_exp_f32_e32 v55, v55
	v_lshlrev_b32_e32 v120, 8, v166
	v_exp_f32_e32 v54, v54
	v_add_co_u32 v120, vcc, v120, v120
	v_cndmask_b32 v55, 0, v55, vcc
	v_add_co_u32 v120, vcc, v120, v120
	v_cndmask_b32 v54, 0, v54, vcc
	s_cbranch_scc1 .Lmixa_near_5
.Lmixa_back_5:
	v_mfma_f32_32x32x16_bf16 v[32:47], v[116:119], v[68:71], v[32:47]
	v_exp_f32_e32 v53, v53
	v_exp_f32_e32 v52, v52
	v_add_co_u32 v120, vcc, v120, v120
	v_cndmask_b32 v53, 0, v53, vcc
	s_nop 0
	v_add_co_u32 v120, vcc, v120, v120
	v_cndmask_b32 v52, 0, v52, vcc
	s_cbranch_scc1 .Lmixa_near_6
.Lmixa_back_6:
	v_exp_f32_e32 v117, v51
	v_exp_f32_e32 v116, v50
	v_add_co_u32 v120, vcc, v120, v120
	v_cndmask_b32 v117, 0, v117, vcc
	v_add_co_u32 v120, vcc, v120, v120
	v_cndmask_b32 v116, 0, v116, vcc
	s_cbranch_scc1 .Lmixa_near_7
.Lmixa_back_7:
	v_mfma_f32_32x32x16_bf16 v[32:47], v[108:111], v[64:67], v[32:47]
	v_exp_f32_e32 v119, v49
	v_exp_f32_e32 v118, v48
	v_add_co_u32 v120, vcc, v120, v120
	v_cndmask_b32 v119, 0, v119, vcc
	v_cvt_pk_bf16_f32 v49, v116, v117
	v_cvt_pk_bf16_f32 v50, v52, v53
	v_cvt_pk_bf16_f32 v51, v54, v55
	v_add_co_u32 v120, vcc, v120, v120
	v_cndmask_b32 v118, 0, v118, vcc
	s_nop 0
	v_cvt_pk_bf16_f32 v48, v118, v119
	s_waitcnt lgkmcnt(0)
	s_nop 0
	v_mfma_f32_32x32x16_bf16 v[0:15], v[112:115], v[48:51], v[0:15]
	s_nop 1
	s_cbranch_scc1 .Lmixa_near_8
.Lmixa_back_8:
	v_lshrrev_b32_e32 v108, v147, v164
	v_exp_f32_e32 v47, v47
	v_lshlrev_b32_e32 v108, 8, v108
	v_exp_f32_e32 v46, v46
	v_add_co_u32 v108, vcc, v108, v108
	v_cndmask_b32 v47, 0, v47, vcc
	v_add_co_u32 v108, vcc, v108, v108
	v_cndmask_b32 v46, 0, v46, vcc
	s_cbranch_scc1 .Lmixa_near_9
.Lmixa_back_9:
	v_exp_f32_e32 v45, v45
	v_exp_f32_e32 v44, v44
	v_add_co_u32 v108, vcc, v108, v108
	v_cndmask_b32 v45, 0, v45, vcc
	s_nop 0
	v_add_co_u32 v108, vcc, v108, v108
	v_cndmask_b32 v44, 0, v44, vcc
	v_mfma_f32_32x32x16_bf16 v[16:31], v[104:107], v[48:51], v[16:31]
	s_cbranch_scc1 .Lmixa_near_10
.Lmixa_back_10:
	v_exp_f32_e32 v49, v43
	v_exp_f32_e32 v48, v42
	v_add_co_u32 v108, vcc, v108, v108
	v_cndmask_b32 v49, 0, v49, vcc
	v_add_co_u32 v108, vcc, v108, v108
	v_cndmask_b32 v48, 0, v48, vcc
	s_cbranch_scc1 .Lmixa_near_11
.Lmixa_back_11:
	v_exp_f32_e32 v51, v41
	v_exp_f32_e32 v50, v40
	v_cvt_pk_bf16_f32 v40, v56, v57
	v_cvt_pk_bf16_f32 v41, v58, v59
	v_cvt_pk_bf16_f32 v42, v60, v61
	v_cvt_pk_bf16_f32 v43, v62, v63
	v_add_co_u32 v108, vcc, v108, v108
	v_cndmask_b32 v51, 0, v51, vcc
	s_nop 0
	v_add_co_u32 v108, vcc, v108, v108
	v_cndmask_b32 v50, 0, v50, vcc
	s_nop 0
	v_mfma_f32_32x32x16_bf16 v[0:15], v[100:103], v[40:43], v[0:15]
	s_cbranch_scc1 .Lmixa_near_12
.Lmixa_back_12:
	v_exp_f32_e32 v39, v39
	v_lshlrev_b32_e32 v100, 8, v108
	v_exp_f32_e32 v38, v38
	v_add_co_u32 v100, vcc, v100, v100
	v_cndmask_b32 v39, 0, v39, vcc
	v_add_co_u32 v100, vcc, v100, v100
	v_cndmask_b32 v38, 0, v38, vcc
	s_cbranch_scc1 .Lmixa_near_13
.Lmixa_back_13:
	v_exp_f32_e32 v37, v37
	v_exp_f32_e32 v36, v36
	v_add_co_u32 v100, vcc, v100, v100
	v_cndmask_b32 v37, 0, v37, vcc
	s_nop 0
	v_add_co_u32 v100, vcc, v100, v100
	v_cndmask_b32 v36, 0, v36, vcc
	v_mfma_f32_32x32x16_bf16 v[16:31], v[96:99], v[40:43], v[16:31]
	s_cbranch_scc1 .Lmixa_near_14
.Lmixa_back_14:
	v_exp_f32_e32 v35, v35
	v_exp_f32_e32 v34, v34
	v_add_co_u32 v100, vcc, v100, v100
	v_cndmask_b32 v35, 0, v35, vcc
	v_add_co_u32 v100, vcc, v100, v100
	v_cndmask_b32 v34, 0, v34, vcc
	s_cbranch_scc0 .LBB0_108
	ds_read2_b32 v[40:41], v162 offset0:32 offset1:33
	s_waitcnt lgkmcnt(0)
	v_pk_add_f32 v[32:33], v[32:33], v[40:41]
	s_branch .LBB0_108
.Lmixa_near_0:
	ds_read2_b32 v[38:39], v162 offset0:22 offset1:23
	s_waitcnt lgkmcnt(0)
	v_pk_add_f32 v[62:63], v[62:63], v[38:39]
	s_branch .Lmixa_back_0
.Lmixa_near_1:
	ds_read2_b32 v[38:39], v162 offset0:20 offset1:21
	s_waitcnt lgkmcnt(0)
	v_pk_add_f32 v[60:61], v[60:61], v[38:39]
	s_branch .Lmixa_back_1

; template <int DQK, bool MIXA, bool PIPE>
; DI void attn_item(const Params& P, int layer, char* smem, int b, int h, int qt) {
;     ...
;         if (MIXA) {
;           if (near) {
;             const int kl = 16 * (r0 >> 3) + 8 * H + (r0 & 7);
;             const int rel = kc * 64 + 32 * kb + kl - qpos;
;             xv2.x += biasT[rel + 192];
;             xv2.y += biasT[rel + 193];
;           }
.Lmixa_near_7:
	ds_read2_b32 v[226:227], v162 offset1:1
	s_waitcnt lgkmcnt(0)
	v_pk_add_f32 v[48:49], v[48:49], v[226:227]
	s_branch .Lmixa_back_7

; template <int DQK, bool MIXA, bool PIPE>
; DI void attn_item(const Params& P, int layer, char* smem, int b, int h, int qt) {
;     ...
;         if (MIXA) {
;           if (near) {
;             const int kl = 16 * (r0 >> 3) + 8 * H + (r0 & 7);
;             const int rel = kc * 64 + 32 * kb + kl - qpos;
;             xv2.x += biasT[rel + 192];
;             xv2.y += biasT[rel + 193];
;           }
.Lmixa_near_11:
	ds_read2_b32 v[226:227], v162 offset0:48 offset1:49
	s_waitcnt lgkmcnt(0)
	v_pk_add_f32 v[40:41], v[40:41], v[226:227]
	s_branch .Lmixa_back_11

; template <int DQK, bool MIXA, bool PIPE>
; DI void attn_item(const Params& P, int layer, char* smem, int b, int h, int qt) {
;     ...
;         for (int s = 0; s < NS; ++s) kf[kb][s] = *(const bf16x8*)(Ks + (32 * kb + pr) * KROWB + (((2 * s + H) ^ swk) << 4));
;       __builtin_amdgcn_sched_barrier(0);
;       f32x16 sacc[2];
; #pragma unroll
;       for (int kb = 0; kb < 2; ++kb)
; #pragma unroll
;         for (int i = 0; i < 16; ++i) sacc[kb][i] = 0.f;
; #pragma unroll
;       for (int s = 0; s < NS; ++s) sacc[0] = __builtin_amdgcn_mfma_f32_32x32x16_bf16(kf[0][s], qf[s], sacc[0], 0, 0, 0);
;       bf16x8 vf[2][2][2];
; #pragma unroll
;       for (int d = 0; d < 2; ++d)
; #pragma unroll
;         for (int kb = 0; kb < 2; ++kb)
; #pragma unroll
;           for (int s2 = 0; s2 < 2; ++s2)
;             vf[d][kb][s2] = *(const bf16x8*)(Vs + (d * 32 + l31) * 128 + (((4 * kb + 2 * s2 + H) ^ swv) << 4));
;       __builtin_amdgcn_sched_barrier(0);
;       const bool near = MIXA && (kc >= cw - 2);
;       f32x2 ls2 = {0.f, 0.f};
;       const f32x2 sl2v = {sl2, sl2}, mfixv = {mfix, mfix};
;       unsigned pkw[2][2][4];
;       unsigned mrot[2];
; #pragma unroll
;       for (int kb = 0; kb < 2; ++kb) mrot[kb] = MIXA ? ((mw[kb] >> (8 * H)) << 8) : 0u;
;       auto chunk = [&](int kb, int c) __attribute__((always_inline)) {
;         const int s2 = 1 - (c >> 2), e = 3 - (c & 3);
;         const int r0 = 8 * s2 + 2 * e;
;         if (MIXA && c == 4) mrot[kb] <<= 8;
;         f32x2 xv2 = {sacc[kb][r0], sacc[kb][r0 + 1]};
;         xv2 = xv2 * sl2v - mfixv;
;         if (MIXA) {
;           if (near) {
;             const int kl = 16 * (r0 >> 3) + 8 * H + (r0 & 7);
;             const int rel = kc * 64 + 32 * kb + kl - qpos;
;             xv2.x += biasT[rel + 192];
;             xv2.y += biasT[rel + 193];
;           }
;         }
;         f32x2 p2 = {__builtin_amdgcn_exp2f(xv2.x), __builtin_amdgcn_exp2f(xv2.y)};
;         if (MIXA) {
;           float px = p2.x, py = p2.y;
;           asm volatile("v_add_co_u32 %0, vcc, %0, %0\n\tv_cndmask_b32 %1, 0, %1, vcc" : "+v"(mrot[kb]), "+v"(py) : : "vcc");
;           asm volatile("v_add_co_u32 %0, vcc, %0, %0\n\tv_cndmask_b32 %1, 0, %1, vcc" : "+v"(mrot[kb]), "+v"(px) : : "vcc");
;           p2.x = px; p2.y = py;
;         }
;         ls2 += p2;
;         pkw[kb][s2][e] = pk2(p2.x, p2.y);
;       };
.LBB0_145:
	s_or_b64 exec, exec, s[58:59]
	s_and_saveexec_b64 s[44:45], s[56:57]
	s_cbranch_execz .LBB0_74
	v_add_u32_e32 v32, v36, v155
	v_add_u32_e32 v33, v32, v157
	v_add_u32_e32 v37, v32, v158
	v_add_u32_e32 v46, v32, v159
	v_add_u32_e32 v47, v32, v160
	ds_read_b128 v[38:41], v33
	ds_read_b128 v[32:35], v33 offset:4096
	ds_read_b128 v[42:45], v37
	ds_read_b128 v[120:123], v37 offset:4096
	ds_read_b128 v[80:83], v46
	ds_read_b128 v[116:119], v46 offset:4096
	ds_read_b128 v[84:87], v47
	ds_read_b128 v[108:111], v47 offset:4096
	s_waitcnt lgkmcnt(7)
	v_mfma_f32_32x32x16_bf16 v[48:63], v[38:41], v[76:79], v[228:243]
	v_add_u32_e32 v36, v36, v150
	v_add_u32_e32 v37, v36, v154
	v_add_u32_e32 v38, v36, v153
	v_add_u32_e32 v39, v36, v151
	v_add_u32_e32 v36, v36, v152
	ds_read_b128 v[112:115], v37 offset:8192
	ds_read_b128 v[100:103], v38 offset:8192
	s_waitcnt lgkmcnt(7)
	v_mfma_f32_32x32x16_bf16 v[48:63], v[42:45], v[72:75], v[48:63]
	s_waitcnt lgkmcnt(5)
	v_mfma_f32_32x32x16_bf16 v[48:63], v[80:83], v[68:71], v[48:63]
	ds_read_b128 v[80:83], v39 offset:8192
	s_waitcnt lgkmcnt(4)
	v_mfma_f32_32x32x16_bf16 v[48:63], v[84:87], v[64:67], v[48:63]
	ds_read_b128 v[84:87], v36 offset:8192
	ds_read_b128 v[104:107], v37 offset:12288
	ds_read_b128 v[96:99], v38 offset:12288
	ds_read_b128 v[92:95], v39 offset:12288
	ds_read_b128 v[88:91], v36 offset:12288
	v_add3_u32 v38, v144, v147, 64
	v_cmp_ge_i32_e64 s[42:43], v149, v148
	s_nop 4
	v_sub_u32_e32 v124, v38, v124
	s_and_saveexec_b64 s[18:19], s[42:43]
	s_cbranch_execz .LBB0_148
	v_lshl_add_u32 v38, v124, 2, v181
	ds_read2_b32 v[38:39], v38 offset1:1
	s_waitcnt lgkmcnt(0)
	v_pk_add_f32 v[62:63], v[62:63], v[38:39]
.LBB0_148:
	s_or_b64 exec, exec, s[18:19]
	v_exp_f32_e32 v62, v62
	v_lshrrev_b32_e32 v36, v147, v156
	v_exp_f32_e32 v63, v63
	v_lshlrev_b32_e32 v130, 8, v36
	v_add_co_u32 v130, vcc, v130, v130
	v_cndmask_b32 v63, 0, v63, vcc
	v_add_co_u32 v130, vcc, v130, v130
	v_cndmask_b32 v62, 0, v62, vcc
	s_and_saveexec_b64 s[18:19], s[42:43]
	s_cbranch_execz .LBB0_150
	v_lshl_add_u32 v38, v124, 2, v182
	ds_read2_b32 v[38:39], v38 offset1:1
	s_waitcnt lgkmcnt(0)
	v_pk_add_f32 v[60:61], v[60:61], v[38:39]
.LBB0_150:
	s_or_b64 exec, exec, s[18:19]
	v_exp_f32_e32 v61, v61
	v_exp_f32_e32 v60, v60
	v_mfma_f32_32x32x16_bf16 v[32:47], v[32:35], v[76:79], v[228:243]
	v_add_co_u32 v130, vcc, v130, v130
	v_cndmask_b32 v61, 0, v61, vcc
	s_nop 0
	v_add_co_u32 v130, vcc, v130, v130
	v_cndmask_b32 v60, 0, v60, vcc
	s_and_saveexec_b64 s[18:19], s[42:43]
	s_cbranch_execz .LBB0_152
	v_lshl_add_u32 v76, v124, 2, v183
	ds_read2_b32 v[76:77], v76 offset1:1
	s_waitcnt lgkmcnt(0)
	v_pk_add_f32 v[58:59], v[58:59], v[76:77]
.LBB0_152:
	s_or_b64 exec, exec, s[18:19]
	v_exp_f32_e32 v59, v59
	v_exp_f32_e32 v58, v58
	v_add_co_u32 v130, vcc, v130, v130
	v_cndmask_b32 v59, 0, v59, vcc
	v_add_co_u32 v130, vcc, v130, v130
	v_cndmask_b32 v58, 0, v58, vcc
	s_and_saveexec_b64 s[18:19], s[42:43]
	s_cbranch_execz .LBB0_154
	v_lshl_add_u32 v76, v124, 2, v184
	ds_read2_b32 v[76:77], v76 offset1:1
	s_waitcnt lgkmcnt(0)
	v_pk_add_f32 v[56:57], v[56:57], v[76:77]
.LBB0_154:
	s_or_b64 exec, exec, s[18:19]
	v_mfma_f32_32x32x16_bf16 v[32:47], v[120:123], v[72:75], v[32:47]
	v_exp_f32_e32 v57, v57
	v_exp_f32_e32 v56, v56
	v_add_co_u32 v130, vcc, v130, v130
	v_cndmask_b32 v57, 0, v57, vcc
	s_nop 0
	v_add_co_u32 v130, vcc, v130, v130
	v_cndmask_b32 v56, 0, v56, vcc
	s_and_saveexec_b64 s[18:19], s[42:43]
	s_cbranch_execz .LBB0_156
	v_lshl_add_u32 v72, v124, 2, v185
	ds_read2_b32 v[72:73], v72 offset1:1
	s_waitcnt lgkmcnt(0)
	v_pk_add_f32 v[54:55], v[54:55], v[72:73]
.LBB0_156:
	s_or_b64 exec, exec, s[18:19]
	v_exp_f32_e32 v55, v55
	v_lshlrev_b32_e32 v72, 8, v130
	v_exp_f32_e32 v54, v54
	v_add_co_u32 v72, vcc, v72, v72
	v_cndmask_b32 v55, 0, v55, vcc
	v_add_co_u32 v72, vcc, v72, v72
	v_cndmask_b32 v54, 0, v54, vcc
	s_and_saveexec_b64 s[18:19], s[42:43]
	s_cbranch_execz .LBB0_158
	v_lshl_add_u32 v73, v124, 2, v186
	ds_read2_b32 v[74:75], v73 offset1:1
	s_waitcnt lgkmcnt(0)
	v_pk_add_f32 v[52:53], v[52:53], v[74:75]
.LBB0_158:
	s_or_b64 exec, exec, s[18:19]
	v_mfma_f32_32x32x16_bf16 v[32:47], v[116:119], v[68:71], v[32:47]
	v_exp_f32_e32 v53, v53
	v_exp_f32_e32 v52, v52
	v_add_co_u32 v72, vcc, v72, v72
	v_cndmask_b32 v53, 0, v53, vcc
	s_nop 0
	v_add_co_u32 v72, vcc, v72, v72
	v_cndmask_b32 v52, 0, v52, vcc
	s_and_saveexec_b64 s[18:19], s[42:43]
	s_cbranch_execz .LBB0_160
	v_lshl_add_u32 v68, v124, 2, v187
	ds_read2_b32 v[68:69], v68 offset1:1
	s_waitcnt lgkmcnt(0)
	v_pk_add_f32 v[50:51], v[50:51], v[68:69]
; template <int DQK, bool MIXA, bool PIPE>
; DI void attn_item(const Params& P, int layer, char* smem, int b, int h, int qt) {
;     ...
;       auto chunk = [&](int kb, int c) __attribute__((always_inline)) {
;         const int s2 = 1 - (c >> 2), e = 3 - (c & 3);
;         const int r0 = 8 * s2 + 2 * e;
;         if (MIXA && c == 4) mrot[kb] <<= 8;
;         f32x2 xv2 = {sacc[kb][r0], sacc[kb][r0 + 1]};
;         xv2 = xv2 * sl2v - mfixv;
;         if (MIXA) {
;           if (near) {
;             const int kl = 16 * (r0 >> 3) + 8 * H + (r0 & 7);
;             const int rel = kc * 64 + 32 * kb + kl - qpos;
;             xv2.x += biasT[rel + 192];
;             xv2.y += biasT[rel + 193];
;           }
;         }
;         f32x2 p2 = {__builtin_amdgcn_exp2f(xv2.x), __builtin_amdgcn_exp2f(xv2.y)};
;         if (MIXA) {
;           float px = p2.x, py = p2.y;
;           asm volatile("v_add_co_u32 %0, vcc, %0, %0\n\tv_cndmask_b32 %1, 0, %1, vcc" : "+v"(mrot[kb]), "+v"(py) : : "vcc");
;           asm volatile("v_add_co_u32 %0, vcc, %0, %0\n\tv_cndmask_b32 %1, 0, %1, vcc" : "+v"(mrot[kb]), "+v"(px) : : "vcc");
;           p2.x = px; p2.y = py;
;         }
;         ls2 += p2;
;         pkw[kb][s2][e] = pk2(p2.x, p2.y);
;       };
;       {
;         int c0 = 0;
; #pragma unroll
;         for (int s = 0; s < NS; ++s) {
;           sacc[1] = __builtin_amdgcn_mfma_f32_32x32x16_bf16(kf[1][s], qf[s], sacc[1], 0, 0, 0);
;           const int cend = (8 * (s + 1)) / NS;
; #pragma unroll
;           for (int c = 0; c < 8; ++c) if (c >= c0 && c < cend) chunk(0, c);
;           c0 = cend;
;           __builtin_amdgcn_sched_barrier(0);
;         }
;       }
;       bf16x8 pf0[2], pf1[2];
; #pragma unroll
;       for (int s2 = 0; s2 < 2; ++s2) { u32x4 t = {pkw[0][s2][0], pkw[0][s2][1], pkw[0][s2][2], pkw[0][s2][3]}; pf0[s2] = __builtin_bit_cast(bf16x8, t); }
; #pragma unroll
;       for (int j = 0; j < 4; ++j) {
;         const int s2 = j >> 1, d = j & 1;
;         o[d] = __builtin_amdgcn_mfma_f32_32x32x16_bf16(vf[d][0][s2], pf0[s2], o[d], 0, 0, 0);
;         chunk(1, 2 * j); chunk(1, 2 * j + 1);
;         __builtin_amdgcn_sched_barrier(0);
;       }
; #pragma unroll
;       for (int s2 = 0; s2 < 2; ++s2) { u32x4 t = {pkw[1][s2][0], pkw[1][s2][1], pkw[1][s2][2], pkw[1][s2][3]}; pf1[s2] = __builtin_bit_cast(bf16x8, t); }
; #pragma unroll
;       for (int j = 0; j < 4; ++j) {
.LBB0_160:
	s_or_b64 exec, exec, s[18:19]
	v_exp_f32_e32 v69, v51
	v_exp_f32_e32 v68, v50
	v_add_co_u32 v72, vcc, v72, v72
	v_cndmask_b32 v69, 0, v69, vcc
	v_add_co_u32 v72, vcc, v72, v72
	v_cndmask_b32 v68, 0, v68, vcc
	s_and_saveexec_b64 s[18:19], s[42:43]
	s_cbranch_execz .LBB0_162
	v_lshl_add_u32 v226, v124, 2, v188
	ds_read2_b32 v[226:227], v226 offset1:1
	s_waitcnt lgkmcnt(0)
	v_pk_add_f32 v[48:49], v[48:49], v[226:227]
.LBB0_162:
	s_or_b64 exec, exec, s[18:19]
	s_waitcnt lgkmcnt(8)
	v_mfma_f32_32x32x16_bf16 v[32:47], v[108:111], v[64:67], v[32:47]
	v_exp_f32_e32 v71, v49
	v_exp_f32_e32 v70, v48
	v_add_co_u32 v72, vcc, v72, v72
	v_cndmask_b32 v71, 0, v71, vcc
	v_cvt_pk_bf16_f32 v49, v68, v69
	v_cvt_pk_bf16_f32 v50, v52, v53
	v_cvt_pk_bf16_f32 v51, v54, v55
	v_add_co_u32 v72, vcc, v72, v72
	v_cndmask_b32 v70, 0, v70, vcc
	s_nop 0
	v_cvt_pk_bf16_f32 v48, v70, v71
	s_waitcnt lgkmcnt(7)
	s_nop 0
	v_mfma_f32_32x32x16_bf16 v[0:15], v[112:115], v[48:51], v[0:15]
	s_nop 1
	s_and_saveexec_b64 s[18:19], s[42:43]
	s_cbranch_execz .LBB0_164
	v_lshl_add_u32 v64, v124, 2, v189
	ds_read2_b32 v[64:65], v64 offset1:1
	s_waitcnt lgkmcnt(0)
	v_pk_add_f32 v[46:47], v[46:47], v[64:65]
.LBB0_164:
	s_or_b64 exec, exec, s[18:19]
	v_lshrrev_b32_e32 v64, v147, v136
	v_exp_f32_e32 v47, v47
	v_lshlrev_b32_e32 v64, 8, v64
	v_exp_f32_e32 v46, v46
	v_add_co_u32 v64, vcc, v64, v64
	v_cndmask_b32 v47, 0, v47, vcc
	v_add_co_u32 v64, vcc, v64, v64
	v_cndmask_b32 v46, 0, v46, vcc
	s_and_saveexec_b64 s[18:19], s[42:43]
	s_cbranch_execz .LBB0_166
	v_lshl_add_u32 v65, v124, 2, v190
	ds_read2_b32 v[66:67], v65 offset1:1
	s_waitcnt lgkmcnt(0)
	v_pk_add_f32 v[44:45], v[44:45], v[66:67]
.LBB0_166:
	s_or_b64 exec, exec, s[18:19]
	v_exp_f32_e32 v45, v45
	v_exp_f32_e32 v44, v44
	v_add_co_u32 v64, vcc, v64, v64
	v_cndmask_b32 v45, 0, v45, vcc
	s_nop 0
	v_add_co_u32 v64, vcc, v64, v64
	v_cndmask_b32 v44, 0, v44, vcc
	s_waitcnt lgkmcnt(3)
	v_mfma_f32_32x32x16_bf16 v[16:31], v[104:107], v[48:51], v[16:31]
	s_and_saveexec_b64 s[18:19], s[42:43]
	s_cbranch_execz .LBB0_168
	v_lshl_add_u32 v48, v124, 2, v191
	ds_read2_b32 v[48:49], v48 offset1:1
	s_waitcnt lgkmcnt(0)
	v_pk_add_f32 v[42:43], v[42:43], v[48:49]
.LBB0_168:
	s_or_b64 exec, exec, s[18:19]
	v_exp_f32_e32 v49, v43
	v_exp_f32_e32 v48, v42
	v_add_co_u32 v64, vcc, v64, v64
	v_cndmask_b32 v49, 0, v49, vcc
	v_add_co_u32 v64, vcc, v64, v64
	v_cndmask_b32 v48, 0, v48, vcc
	s_and_saveexec_b64 s[18:19], s[42:43]
	s_cbranch_execz .LBB0_170
	v_lshl_add_u32 v226, v124, 2, v192
	ds_read2_b32 v[226:227], v226 offset1:1
	s_waitcnt lgkmcnt(0)
	v_pk_add_f32 v[40:41], v[40:41], v[226:227]
.LBB0_170:
	s_or_b64 exec, exec, s[18:19]
	v_exp_f32_e32 v51, v41
	v_exp_f32_e32 v50, v40
	v_cvt_pk_bf16_f32 v40, v56, v57
	v_cvt_pk_bf16_f32 v41, v58, v59
	v_cvt_pk_bf16_f32 v42, v60, v61
	v_cvt_pk_bf16_f32 v43, v62, v63
	v_add_co_u32 v64, vcc, v64, v64
	v_cndmask_b32 v51, 0, v51, vcc
	s_nop 0
	v_add_co_u32 v64, vcc, v64, v64
	v_cndmask_b32 v50, 0, v50, vcc
	s_nop 0
	v_mfma_f32_32x32x16_bf16 v[0:15], v[100:103], v[40:43], v[0:15]
	s_and_saveexec_b64 s[18:19], s[42:43]
	s_cbranch_execz .LBB0_172
	v_lshl_add_u32 v65, v124, 2, v193
	ds_read2_b32 v[66:67], v65 offset1:1
	s_waitcnt lgkmcnt(0)
	v_pk_add_f32 v[38:39], v[38:39], v[66:67]
.LBB0_172:
	s_or_b64 exec, exec, s[18:19]
	v_exp_f32_e32 v39, v39
	v_lshlrev_b32_e32 v64, 8, v64
	v_exp_f32_e32 v38, v38
	v_add_co_u32 v64, vcc, v64, v64
	v_cndmask_b32 v39, 0, v39, vcc
	v_add_co_u32 v64, vcc, v64, v64
	v_cndmask_b32 v38, 0, v38, vcc
	s_and_saveexec_b64 s[18:19], s[42:43]
	s_cbranch_execz .LBB0_174
	v_lshl_add_u32 v65, v124, 2, v194
	ds_read2_b32 v[66:67], v65 offset1:1
	s_waitcnt lgkmcnt(0)
	v_pk_add_f32 v[36:37], v[36:37], v[66:67]
.LBB0_174:
	s_or_b64 exec, exec, s[18:19]
	v_exp_f32_e32 v37, v37
	v_exp_f32_e32 v36, v36
	v_add_co_u32 v64, vcc, v64, v64
	v_cndmask_b32 v37, 0, v37, vcc
	s_nop 0
	v_add_co_u32 v64, vcc, v64, v64
	v_cndmask_b32 v36, 0, v36, vcc
	s_waitcnt lgkmcnt(2)
	v_mfma_f32_32x32x16_bf16 v[16:31], v[96:99], v[40:43], v[16:31]
	s_and_saveexec_b64 s[18:19], s[42:43]
	s_cbranch_execz .LBB0_176
	v_lshl_add_u32 v40, v124, 2, v195
	ds_read2_b32 v[40:41], v40 offset1:1
	s_waitcnt lgkmcnt(0)
	v_pk_add_f32 v[34:35], v[34:35], v[40:41]
.LBB0_176:
	s_or_b64 exec, exec, s[18:19]
	v_exp_f32_e32 v35, v35
	v_exp_f32_e32 v34, v34
	v_add_co_u32 v64, vcc, v64, v64
	v_cndmask_b32 v35, 0, v35, vcc
	v_add_co_u32 v64, vcc, v64, v64
	v_cndmask_b32 v34, 0, v34, vcc
	s_and_saveexec_b64 s[18:19], s[42:43]
	s_cbranch_execz .LBB0_73
	v_lshl_add_u32 v40, v124, 2, v196
	ds_read2_b32 v[40:41], v40 offset1:1
	s_waitcnt lgkmcnt(0)
	v_pk_add_f32 v[32:33], v[32:33], v[40:41]
	s_branch .LBB0_73

; DI unsigned pk2(float a, float b) { f32x2 v = {a, b}; return __builtin_bit_cast(unsigned, __builtin_convertvector(v, bf16x2)); }
; DI float bf2f(unsigned short u) { return __uint_as_float(((unsigned)u) << 16); }
; DI void phase_token_c(const Params& P, int layer, char* smem) {
;     ...
;     {
;       float f[12];
;       float ss = 0.f;
;       const int hd = lane >> 3, j0 = (lane & 7) * 12;
; #pragma unroll
;       for (int e = 0; e < 12; ++e) {
;         const int j = j0 + e;
;         float v;
;         if (j < 64) v = rowbuf[hd * 96 + j];
;         else {
;           const int i = (j - 64) & 15;
;           const float x1 = rowbuf[hd * 96 + 64 + i], x2 = rowbuf[hd * 96 + 80 + i];
;           const float cs = rowbuf[768 + i], sn = rowbuf[784 + i];
;           v = (j < 80) ? (x1 * cs - x2 * sn) : (x1 * sn + x2 * cs);
;         }
;         f[e] = v; ss += v * v;
;       }
;       ss += __shfl_xor(ss, 1); ss += __shfl_xor(ss, 2); ss += __shfl_xor(ss, 4);
;       const float r = rsqrtf(ss * (1.f / 96) + EPS);
;       unsigned o[6];
; #pragma unroll
;       for (int e = 0; e < 6; ++e) o[e] = pk2(f[2 * e] * r * gq[j0 + 2 * e], f[2 * e + 1] * r * gq[j0 + 2 * e + 1]);
;       u32x2* op = (u32x2*)(qr + lane * 12);
;       op[0] = u32x2{o[0], o[1]}; op[1] = u32x2{o[2], o[3]}; op[2] = u32x2{o[4], o[5]};
;     }
;     {
;       float f[12];
;       float ss = 0.f;
;       const int hd = lane >> 3, j0 = (lane & 7) * 12;
; #pragma unroll
;       for (int e = 0; e < 12; ++e) {
;         const int j = j0 + e;
;         const float v = (j < 64) ? bf2f(KV[(size_t)t * 1024 + hd * 128 + j]) : bf2f(Z[(size_t)t * ZLD + C_KR + (j - 64)]);
;         f[e] = v; ss += v * v;
;       }
;       ss += __shfl_xor(ss, 1); ss += __shfl_xor(ss, 2); ss += __shfl_xor(ss, 4);
;       const float r = rsqrtf(ss * (1.f / 96) + EPS);
;       unsigned o[6];
; #pragma unroll
;       for (int e = 0; e < 6; ++e) o[e] = pk2(f[2 * e] * r * gk[j0 + 2 * e], f[2 * e + 1] * r * gk[j0 + 2 * e + 1]);
;       u32x2* op = (u32x2*)(KB + ((size_t)((t / S_) * 8 + hd) * S_ + (t % S_)) * 96 + j0);
;       op[0] = u32x2{o[0], o[1]}; op[1] = u32x2{o[2], o[3]}; op[2] = u32x2{o[4], o[5]};
.LBB0_189:
	s_or_b64 exec, exec, s[0:1]
	s_waitcnt lgkmcnt(0)
	v_mul_f32_e32 v59, v19, v19
	v_fmac_f32_e32 v59, v18, v18
	v_fmac_f32_e32 v59, v2, v2
	v_fmac_f32_e32 v59, v3, v3
	v_fmac_f32_e32 v59, v20, v20
	v_fmac_f32_e32 v59, v21, v21
	v_fmac_f32_e32 v59, v22, v22
	v_fmac_f32_e32 v59, v23, v23
	v_fmac_f32_e32 v59, v24, v24
	v_fmac_f32_e32 v59, v25, v25
	v_fmac_f32_e32 v59, v26, v26
	v_fmac_f32_e32 v59, v27, v27
	ds_bpermute_b32 v60, v30, v59
	s_mov_b32 s3, 0x800000
	s_add_i32 s2, s2, s70
	s_cmpk_gt_i32 s2, 0x1fff
	s_waitcnt lgkmcnt(0)
	v_add_f32_e32 v59, v59, v60
	ds_bpermute_b32 v60, v31, v59
	s_waitcnt lgkmcnt(0)
	v_add_f32_e32 v59, v59, v60
	ds_bpermute_b32 v60, v32, v59
	s_waitcnt lgkmcnt(0)
	v_add_f32_e32 v59, v59, v60
	v_fmamk_f32 v59, v59, 0x3c2aaaab, v165
	v_cmp_gt_f32_e64 s[0:1], s3, v59
	v_mul_f32_e32 v60, 0x4b800000, v59
	s_nop 0
	v_cndmask_b32_e64 v59, v59, v60, s[0:1]
	v_rsq_f32_e32 v59, v59
	s_nop 0
	v_mul_f32_e32 v60, 0x45800000, v59
	v_cndmask_b32_e64 v72, v59, v60, s[0:1]
	v_mul_f32_e32 v72, 0x3e16c740, v72
	global_load_dwordx4 v[60:63], v[8:9], off offset:32
	global_load_dwordx4 v[64:67], v[8:9], off offset:16
	global_load_dwordx4 v[68:71], v[8:9], off
	v_pk_mul_f32 v[18:19], v[18:19], v[72:73] op_sel_hi:[1,0]
	v_pk_mul_f32 v[2:3], v[2:3], v[72:73] op_sel_hi:[1,0]
	s_waitcnt vmcnt(0)
	v_pk_mul_f32 v[18:19], v[68:69], v[18:19]
	v_pk_mul_f32 v[2:3], v[70:71], v[2:3]
	v_cvt_pk_bf16_f32 v18, v18, v19
	v_cvt_pk_bf16_f32 v19, v2, v3
	v_pk_mul_f32 v[2:3], v[20:21], v[72:73] op_sel_hi:[1,0]
	s_nop 0
	v_pk_mul_f32 v[2:3], v[64:65], v[2:3]
	s_nop 0
	v_cvt_pk_bf16_f32 v20, v2, v3
	v_pk_mul_f32 v[2:3], v[22:23], v[72:73] op_sel_hi:[1,0]
	v_pk_mul_f32 v[22:23], v[26:27], v[72:73] op_sel_hi:[1,0]
	v_pk_mul_f32 v[2:3], v[66:67], v[2:3]
	v_pk_mul_f32 v[22:23], v[22:23], v[62:63]
	v_cvt_pk_bf16_f32 v21, v2, v3
	v_pk_mul_f32 v[2:3], v[24:25], v[72:73] op_sel_hi:[1,0]
	s_nop 0
	v_pk_mul_f32 v[2:3], v[60:61], v[2:3]
	s_nop 0
	v_cvt_pk_bf16_f32 v2, v2, v3
	v_cvt_pk_bf16_f32 v3, v22, v23
	v_lshlrev_b32_e32 v22, 1, v4
	v_mov_b32_e32 v23, v137
	v_lshl_add_u64 v[0:1], v[0:1], 0, v[22:23]
	global_store_dwordx4 v[0:1], v[18:21], off
	global_store_dwordx2 v[0:1], v[2:3], off offset:16
	v_mad_i64_i32 v[2:3], s[0:1], v16, s33, v[14:15]
	v_lshlrev_b64 v[0:1], 11, v[16:17]
	s_mov_b64 s[0:1], 0xa001510
	v_lshl_add_u64 v[0:1], v[12:13], 0, v[0:1]
	v_lshl_add_u64 v[18:19], v[2:3], 0, s[0:1]
	v_cndmask_b32_e64 v19, v19, v1, s[40:41]
	v_cndmask_b32_e64 v18, v18, v0, s[40:41]
	global_load_dwordx2 v[26:27], v[18:19], off
	s_mov_b64 s[0:1], 0xa001518
	v_lshl_add_u64 v[0:1], v[0:1], 0, 8
	v_lshl_add_u64 v[2:3], v[2:3], 0, s[0:1]
	v_cndmask_b32_e64 v1, v3, v1, s[46:47]
	v_cndmask_b32_e64 v0, v2, v0, s[46:47]
	global_load_dwordx4 v[0:3], v[0:1], off
	s_nop 0
	global_load_dwordx4 v[18:21], v[10:11], off offset:32
	global_load_dwordx4 v[22:25], v[10:11], off offset:16
	global_load_dwordx4 v[60:63], v[10:11], off
	s_waitcnt vmcnt(4)
	v_and_b32_e32 v77, 0xffff0000, v27
	v_lshlrev_b32_e32 v76, 16, v27
	v_and_b32_e32 v27, 0xffff0000, v26
	v_lshlrev_b32_e32 v26, 16, v26
	v_pk_mul_f32 v[80:81], v[26:27], v[26:27]
	v_pk_mul_f32 v[78:79], v[76:77], v[76:77]
	v_add_f32_e32 v17, v80, v81
	s_waitcnt vmcnt(3)
	v_and_b32_e32 v75, 0xffff0000, v0
	v_lshlrev_b32_e32 v74, 16, v0
	v_add_f32_e32 v17, v17, v78
	v_and_b32_e32 v71, 0xffff0000, v1
	v_lshlrev_b32_e32 v70, 16, v1
	v_pk_mul_f32 v[0:1], v[74:75], v[74:75]
	v_add_f32_e32 v17, v17, v79
	v_add_f32_e32 v0, v17, v0
	v_pk_mul_f32 v[72:73], v[70:71], v[70:71]
	v_add_f32_e32 v0, v0, v1
	v_and_b32_e32 v69, 0xffff0000, v2
	v_lshlrev_b32_e32 v68, 16, v2
	v_add_f32_e32 v0, v0, v72
	v_and_b32_e32 v65, 0xffff0000, v3
	v_lshlrev_b32_e32 v64, 16, v3
	v_pk_mul_f32 v[2:3], v[68:69], v[68:69]
	v_add_f32_e32 v0, v0, v73
	v_add_f32_e32 v0, v0, v2
	v_pk_mul_f32 v[66:67], v[64:65], v[64:65]
	v_add_f32_e32 v0, v0, v3
	v_add_f32_e32 v0, v0, v66
	v_add_f32_e32 v0, v0, v67
	ds_bpermute_b32 v1, v30, v0
	v_ashrrev_i32_e32 v17, 31, v16
	v_lshrrev_b32_e32 v17, 18, v17
	v_add_u32_e32 v17, v16, v17
	v_ashrrev_i32_e32 v17, 14, v17
	s_waitcnt lgkmcnt(0)
	v_add_f32_e32 v0, v0, v1
	ds_bpermute_b32 v1, v31, v0
	s_waitcnt lgkmcnt(0)
	v_add_f32_e32 v0, v0, v1
	ds_bpermute_b32 v1, v32, v0
	s_waitcnt lgkmcnt(0)
	v_add_f32_e32 v0, v0, v1
	v_fmamk_f32 v0, v0, 0x3c2aaaab, v165
	v_cmp_gt_f32_e64 s[0:1], s3, v0
	v_mul_f32_e32 v1, 0x4b800000, v0
	s_nop 0
	v_cndmask_b32_e64 v0, v0, v1, s[0:1]
	v_rsq_f32_e32 v0, v0
	s_nop 0
	v_mul_f32_e32 v1, 0x45800000, v0
	v_cndmask_b32_e64 v66, v0, v1, s[0:1]
	v_pk_mul_f32 v[0:1], v[66:67], v[26:27] op_sel_hi:[0,1]
	v_pk_mul_f32 v[2:3], v[66:67], v[76:77] op_sel_hi:[0,1]
	s_waitcnt vmcnt(0)
	v_pk_mul_f32 v[0:1], v[60:61], v[0:1]
	v_pk_mul_f32 v[2:3], v[62:63], v[2:3]
	v_cvt_pk_bf16_f32 v0, v0, v1
	v_cvt_pk_bf16_f32 v1, v2, v3
	v_pk_mul_f32 v[2:3], v[66:67], v[74:75] op_sel_hi:[0,1]
	v_pk_mul_f32 v[2:3], v[22:23], v[2:3]
	v_pk_mul_f32 v[22:23], v[66:67], v[70:71] op_sel_hi:[0,1]
	v_pk_mul_f32 v[22:23], v[24:25], v[22:23]
	v_cvt_pk_bf16_f32 v2, v2, v3
	v_cvt_pk_bf16_f32 v3, v22, v23
	v_pk_mul_f32 v[22:23], v[66:67], v[68:69] op_sel_hi:[0,1]
	v_pk_mul_f32 v[18:19], v[18:19], v[22:23]
	v_pk_mul_f32 v[22:23], v[66:67], v[64:65] op_sel_hi:[0,1]
	v_pk_mul_f32 v[20:21], v[20:21], v[22:23]
	v_cvt_pk_bf16_f32 v18, v18, v19
	v_cvt_pk_bf16_f32 v19, v20, v21
	v_lshl_or_b32 v20, v17, 3, v29
	v_mul_i32_i24_e32 v17, 0x4000, v17
	v_ashrrev_i32_e32 v21, 31, v20
	v_sub_u32_e32 v22, v16, v17
	v_lshlrev_b64 v[20:21], 14, v[20:21]
	v_ashrrev_i32_e32 v23, 31, v22
	v_lshl_add_u64 v[20:21], v[20:21], 0, v[22:23]
	v_mad_u64_u32 v[22:23], s[0:1], v20, s72, v[6:7]
	v_mad_i32_i24 v23, v21, s72, v23
	v_add_u32_e32 v16, s26, v16
	global_store_dwordx4 v[22:23], v[0:3], off
	global_store_dwordx2 v[22:23], v[18:19], off offset:16
	s_barrier
	s_cbranch_scc1 .LBB0_244

; DI unsigned pk2(float a, float b) { f32x2 v = {a, b}; return __builtin_bit_cast(unsigned, __builtin_convertvector(v, bf16x2)); }
; DI float bflo(unsigned u) { return __uint_as_float(u << 16); }
; DI float bfhi(unsigned u) { return __uint_as_float(u & 0xffff0000u); }
; DI void phase_token_a(const Params& P, int layer, char* smem) {
;     ...
;     for (int which = 0; which < 2; ++which) {
;       const float* g = which ? gk : gq;
;       u32x4* p = (u32x4*)(zr + (which ? C_KA : C_QA) + lane * 8);
;       u32x4 u = *p;
;       float f[8] = {bflo(u.x), bfhi(u.x), bflo(u.y), bfhi(u.y), bflo(u.z), bfhi(u.z), bflo(u.w), bfhi(u.w)};
;       float ss = 0.f;
; #pragma unroll
;       for (int j = 0; j < 8; ++j) ss += f[j] * f[j];
;       ss += __shfl_xor(ss, 1); ss += __shfl_xor(ss, 2); ss += __shfl_xor(ss, 4);
;       const float r = rsqrtf(ss * (1.f / 64) + EPS);
;       const int c0 = (lane & 7) * 8;
; #pragma unroll
;       for (int j = 0; j < 8; ++j) f[j] = f[j] * r * g[c0 + j];
;       u.x = pk2(f[0], f[1]); u.y = pk2(f[2], f[3]); u.z = pk2(f[4], f[5]); u.w = pk2(f[6], f[7]);
;       *p = u;
;     }
;     {
;       unsigned* p = (unsigned*)(zr + C_CQ + lane * 6);
;       unsigned u0 = p[0], u1 = p[1], u2 = p[2];
;       float f[6] = {bflo(u0), bfhi(u0), bflo(u1), bfhi(u1), bflo(u2), bfhi(u2)};
;       float ss = 0.f;
; #pragma unroll
;       for (int j = 0; j < 6; ++j) ss += f[j] * f[j];
;       ss = wave_sum(ss);
;       const float r = rsqrtf(ss * (1.f / 384) + EPS);
; #pragma unroll
;       for (int j = 0; j < 6; ++j) f[j] = f[j] * r * gcq[lane * 6 + j];
;       p[0] = pk2(f[0], f[1]); p[1] = pk2(f[2], f[3]); p[2] = pk2(f[4], f[5]);
;     }
.LBB0_422:
	v_mov_b64_e32 v[0:1], s[86:87]
	v_mad_i64_i32 v[22:23], s[0:1], v36, s33, v[0:1]
	v_lshl_add_u64 v[26:27], v[22:23], 0, v[136:137]
	global_load_dwordx4 v[44:47], v[26:27], off
	global_load_dwordx4 v[0:3], v[8:9], off offset:16
	global_load_dwordx4 v[4:7], v[8:9], off
	s_mov_b32 s0, 0x358637bd
	v_mov_b32_e32 v21, v137
	s_waitcnt vmcnt(0)
	v_lshlrev_b32_e32 v28, 16, v47
	v_and_b32_e32 v29, 0xffff0000, v47
	v_lshlrev_b32_e32 v30, 16, v46
	v_and_b32_e32 v31, 0xffff0000, v46
	v_lshlrev_b32_e32 v32, 16, v45
	v_and_b32_e32 v33, 0xffff0000, v45
	v_lshlrev_b32_e32 v34, 16, v44
	v_and_b32_e32 v35, 0xffff0000, v44
	global_load_dwordx4 v[44:47], v[26:27], off offset:1024
	v_pk_mul_f32 v[52:53], v[34:35], v[34:35]
	v_pk_mul_f32 v[50:51], v[32:33], v[32:33]
	v_mov_b32_e32 v67, v52
	v_pk_mul_f32 v[48:49], v[30:31], v[30:31]
	v_pk_mul_f32 v[24:25], v[28:29], v[28:29]
	s_waitcnt vmcnt(0)
	v_lshlrev_b32_e32 v64, 16, v44
	v_and_b32_e32 v65, 0xffff0000, v44
	v_lshlrev_b32_e32 v60, 16, v45
	v_and_b32_e32 v61, 0xffff0000, v45
	v_pk_mul_f32 v[44:45], v[64:65], v[64:65]
	v_pk_mul_f32 v[62:63], v[60:61], v[60:61]
	v_mov_b32_e32 v66, v44
	v_mov_b32_e32 v52, v45
	v_lshlrev_b32_e32 v58, 16, v46
	v_and_b32_e32 v59, 0xffff0000, v46
	v_pk_add_f32 v[44:45], v[66:67], v[52:53]
	v_mov_b32_e32 v52, v62
	v_mov_b32_e32 v53, v50
	v_lshlrev_b32_e32 v54, 16, v47
	v_and_b32_e32 v55, 0xffff0000, v47
	v_pk_mul_f32 v[46:47], v[58:59], v[58:59]
	v_pk_add_f32 v[44:45], v[52:53], v[44:45]
	v_mov_b32_e32 v50, v63
	v_pk_add_f32 v[44:45], v[50:51], v[44:45]
	v_mov_b32_e32 v50, v46
	v_mov_b32_e32 v51, v48
	v_pk_mul_f32 v[56:57], v[54:55], v[54:55]
	v_pk_add_f32 v[44:45], v[50:51], v[44:45]
	v_mov_b32_e32 v48, v47
	v_pk_add_f32 v[44:45], v[48:49], v[44:45]
	v_mov_b32_e32 v46, v56
	v_mov_b32_e32 v47, v24
	v_pk_add_f32 v[44:45], v[46:47], v[44:45]
	v_mov_b32_e32 v24, v57
	v_pk_add_f32 v[24:25], v[24:25], v[44:45]
	ds_bpermute_b32 v45, v37, v25
	ds_bpermute_b32 v44, v37, v24
	s_waitcnt lgkmcnt(0)
	v_pk_add_f32 v[24:25], v[24:25], v[44:45]
	ds_bpermute_b32 v45, v38, v25
	ds_bpermute_b32 v44, v38, v24
	s_waitcnt lgkmcnt(0)
	v_pk_add_f32 v[24:25], v[24:25], v[44:45]
	ds_bpermute_b32 v45, v39, v25
	ds_bpermute_b32 v44, v39, v24
	s_waitcnt lgkmcnt(0)
	v_pk_add_f32 v[44:45], v[24:25], v[44:45]
	v_mov_b64_e32 v[24:25], s[0:1]
	s_mov_b32 s0, 0x3c800000
	v_pk_fma_f32 v[44:45], v[44:45], s[0:1], v[24:25] op_sel_hi:[1,0,0]
	s_nop 0
	v_mul_f32_e32 v17, 0x4b800000, v45
	v_cmp_gt_f32_e64 s[0:1], s6, v45
	v_cmp_gt_f32_e32 vcc, s6, v44
	s_nop 0
	v_cndmask_b32_e64 v17, v45, v17, s[0:1]
	v_rsq_f32_e32 v17, v17
	s_nop 0
	v_mul_f32_e32 v19, 0x45800000, v17
	v_cndmask_b32_e64 v46, v17, v19, s[0:1]
	v_mul_f32_e32 v46, 0x3e38aa3b, v46
	v_pk_mul_f32 v[30:31], v[46:47], v[30:31] op_sel_hi:[0,1]
	v_pk_mul_f32 v[34:35], v[46:47], v[34:35] op_sel_hi:[0,1]
	v_pk_mul_f32 v[32:33], v[46:47], v[32:33] op_sel_hi:[0,1]
	v_pk_mul_f32 v[30:31], v[0:1], v[30:31]
	v_pk_mul_f32 v[0:1], v[46:47], v[28:29] op_sel_hi:[0,1]
	v_pk_mul_f32 v[4:5], v[4:5], v[34:35]
	v_pk_mul_f32 v[6:7], v[6:7], v[32:33]
	v_pk_mul_f32 v[28:29], v[2:3], v[0:1]
	v_cvt_pk_bf16_f32 v0, v4, v5
	v_cvt_pk_bf16_f32 v1, v6, v7
	v_cvt_pk_bf16_f32 v2, v30, v31
	v_cvt_pk_bf16_f32 v3, v28, v29
	global_store_dwordx4 v[26:27], v[0:3], off
	global_load_dwordx4 v[0:3], v[10:11], off offset:16
	s_nop 0
	global_load_dwordx4 v[4:7], v[10:11], off
	v_mul_f32_e32 v17, 0x4b800000, v44
	v_cndmask_b32_e32 v17, v44, v17, vcc
	v_rsq_f32_e32 v17, v17
	s_mov_b32 s0, 0x3b800000
	s_mov_b32 s1, 0x3b2aaaab
	v_mul_f32_e32 v19, 0x45800000, v17
	v_cndmask_b32_e32 v28, v17, v19, vcc
	v_pk_mul_f32 v[30:31], v[28:29], v[64:65] op_sel_hi:[0,1]
	v_mov_b32_e32 v17, v137
	v_mov_b32_e32 v19, v137
	s_waitcnt vmcnt(0)
	v_pk_mul_f32 v[4:5], v[4:5], v[30:31]
	v_pk_mul_f32 v[30:31], v[28:29], v[60:61] op_sel_hi:[0,1]
	v_pk_mul_f32 v[6:7], v[6:7], v[30:31]
	v_pk_mul_f32 v[30:31], v[28:29], v[58:59] op_sel_hi:[0,1]
	v_pk_mul_f32 v[30:31], v[0:1], v[30:31]
	v_pk_mul_f32 v[0:1], v[28:29], v[54:55] op_sel_hi:[0,1]
	v_pk_mul_f32 v[28:29], v[2:3], v[0:1]
	v_cvt_pk_bf16_f32 v0, v4, v5
	v_cvt_pk_bf16_f32 v1, v6, v7
	v_cvt_pk_bf16_f32 v2, v30, v31
	v_cvt_pk_bf16_f32 v3, v28, v29
	global_store_dwordx4 v[26:27], v[0:3], off offset:1024
	s_nop 1
	v_lshl_add_u64 v[0:1], v[22:23], 0, v[16:17]
	v_add_co_u32_e32 v26, vcc, s3, v0
	s_nop 1
	v_addc_co_u32_e32 v27, vcc, 0, v1, vcc
	global_load_dwordx3 v[0:2], v[26:27], off offset:144
	s_waitcnt vmcnt(0)
	v_and_b32_e32 v29, 0xffff0000, v0
	v_lshlrev_b32_e32 v28, 16, v0
	v_mul_f32_e32 v4, v29, v29
	v_lshlrev_b32_e32 v30, 16, v1
	v_and_b32_e32 v31, 0xffff0000, v1
	v_pk_fma_f32 v[4:5], v[28:29], v[28:29], v[4:5] op_sel_hi:[1,1,0]
	v_lshlrev_b32_e32 v32, 16, v2
	v_pk_fma_f32 v[48:49], v[30:31], v[30:31], v[4:5]
	v_lshl_add_u64 v[4:5], v[22:23], 0, v[18:19]
	v_add_co_u32_e32 v50, vcc, s3, v4
	v_and_b32_e32 v33, 0xffff0000, v2
	s_nop 0
	v_addc_co_u32_e32 v51, vcc, 0, v5, vcc
	global_load_dwordx2 v[46:47], v[12:13], off offset:16
	global_load_dwordx4 v[0:3], v[12:13], off
	global_load_dwordx2 v[4:5], v[50:51], off offset:912
	v_pk_mul_f32 v[44:45], v[30:31], v[30:31]
	v_pk_mul_f32 v[34:35], v[32:33], v[32:33]
	s_waitcnt vmcnt(0)
	v_lshlrev_b32_e32 v52, 16, v5
	v_and_b32_e32 v53, 0xffff0000, v5
	v_lshlrev_b32_e32 v56, 16, v4
	v_and_b32_e32 v57, 0xffff0000, v4
	global_load_dwordx4 v[4:7], v[14:15], off
	v_pk_mul_f32 v[58:59], v[56:57], v[56:57]
	v_pk_mul_f32 v[54:55], v[52:53], v[52:53]
	v_mov_b32_e32 v44, v58
	v_pk_mov_b32 v[48:49], v[58:59], v[48:49] op_sel:[1,0]
	s_nop 0
	v_pk_add_f32 v[44:45], v[44:45], v[48:49]
	v_mov_b32_e32 v48, v54
	v_mov_b32_e32 v49, v34
	v_pk_add_f32 v[44:45], v[48:49], v[44:45]
	v_mov_b32_e32 v34, v55
	v_pk_add_f32 v[34:35], v[34:35], v[44:45]
	ds_bpermute_b32 v45, v40, v35
	ds_bpermute_b32 v44, v40, v34
	s_waitcnt lgkmcnt(0)
; DI unsigned pk2(float a, float b) { f32x2 v = {a, b}; return __builtin_bit_cast(unsigned, __builtin_convertvector(v, bf16x2)); }
; DI float bf2f(unsigned short u) { return __uint_as_float(((unsigned)u) << 16); }
; DI float bflo(unsigned u) { return __uint_as_float(u << 16); }
; DI float bfhi(unsigned u) { return __uint_as_float(u & 0xffff0000u); }
; DI void phase_token_a(const Params& P, int layer, char* smem) {
;     ...
;       ss = wave_sum(ss);
;       const float r = rsqrtf(ss * (1.f / 384) + EPS);
; #pragma unroll
;       for (int j = 0; j < 6; ++j) f[j] = f[j] * r * gcq[lane * 6 + j];
;       p[0] = pk2(f[0], f[1]); p[1] = pk2(f[2], f[3]); p[2] = pk2(f[4], f[5]);
;     }
;     {
;       u32x2* p = (u32x2*)(zr + C_CKV + lane * 4);
;       u32x2 u = *p;
;       float f[4] = {bflo(u.x), bfhi(u.x), bflo(u.y), bfhi(u.y)};
;       float ss = f[0] * f[0] + f[1] * f[1] + f[2] * f[2] + f[3] * f[3];
;       ss = wave_sum(ss);
;       const float r = rsqrtf(ss * (1.f / 256) + EPS);
; #pragma unroll
;       for (int j = 0; j < 4; ++j) f[j] = f[j] * r * gckv[lane * 4 + j];
;       u.x = pk2(f[0], f[1]); u.y = pk2(f[2], f[3]);
;       *p = u;
;     }
;     {
;       const int i = lane & 15;
;       const float x1 = bf2f(zr[C_KR + i]), x2 = bf2f(zr[C_KR + 16 + i]);
;       const float inv = powf(10000.f, -(float)i / 16.f);
;       const float ang = (float)(t % S_) * inv;
;       float sn, cs;
;       sincosf(ang, &sn, &cs);
;       const float o1 = x1 * cs - x2 * sn, o2 = x1 * sn + x2 * cs;
	v_pk_add_f32 v[34:35], v[34:35], v[44:45]
	ds_bpermute_b32 v45, v41, v35
	ds_bpermute_b32 v44, v41, v34
	s_waitcnt lgkmcnt(0)
	v_pk_add_f32 v[34:35], v[34:35], v[44:45]
	ds_bpermute_b32 v45, v42, v35
	ds_bpermute_b32 v44, v42, v34
	s_waitcnt lgkmcnt(0)
	v_pk_add_f32 v[34:35], v[34:35], v[44:45]
	ds_bpermute_b32 v45, v39, v35
	ds_bpermute_b32 v44, v39, v34
	s_waitcnt lgkmcnt(0)
	v_pk_add_f32 v[34:35], v[34:35], v[44:45]
	ds_bpermute_b32 v45, v38, v35
	ds_bpermute_b32 v44, v38, v34
	s_waitcnt lgkmcnt(0)
	v_pk_add_f32 v[34:35], v[34:35], v[44:45]
	ds_bpermute_b32 v45, v37, v35
	ds_bpermute_b32 v44, v37, v34
	s_waitcnt lgkmcnt(0)
	v_pk_add_f32 v[34:35], v[34:35], v[44:45]
	s_nop 0
	v_pk_fma_f32 v[24:25], v[34:35], s[0:1], v[24:25] op_sel_hi:[1,1,0]
	s_nop 0
	v_mul_f32_e32 v17, 0x4b800000, v25
	v_cmp_gt_f32_e64 s[0:1], s6, v25
	v_cmp_gt_f32_e32 vcc, s6, v24
	s_nop 0
	v_cndmask_b32_e64 v17, v25, v17, s[0:1]
	v_rsq_f32_e32 v17, v17
	s_nop 0
	v_mul_f32_e32 v19, 0x45800000, v17
	v_cndmask_b32_e64 v34, v17, v19, s[0:1]
	v_pk_mul_f32 v[28:29], v[34:35], v[28:29] op_sel_hi:[0,1]
	v_pk_mul_f32 v[0:1], v[0:1], v[28:29]
	v_pk_mul_f32 v[28:29], v[34:35], v[30:31] op_sel_hi:[0,1]
	v_pk_mul_f32 v[2:3], v[2:3], v[28:29]
	v_pk_mul_f32 v[28:29], v[34:35], v[32:33] op_sel_hi:[0,1]
	v_pk_mul_f32 v[28:29], v[46:47], v[28:29]
	v_cvt_pk_bf16_f32 v0, v0, v1
	v_cvt_pk_bf16_f32 v1, v2, v3
	v_cvt_pk_bf16_f32 v2, v28, v29
	global_store_dwordx3 v[26:27], v[0:2], off offset:144
	s_nop 1
	v_mul_f32_e32 v0, 0x4b800000, v24
	v_cndmask_b32_e32 v0, v24, v0, vcc
	v_rsq_f32_e32 v0, v0
	s_nop 0
	v_mul_f32_e32 v1, 0x45800000, v0
	v_cndmask_b32_e32 v0, v0, v1, vcc
	v_pk_mul_f32 v[2:3], v[0:1], v[56:57] op_sel_hi:[0,1]
	v_pk_mul_f32 v[0:1], v[0:1], v[52:53] op_sel_hi:[0,1]
	s_waitcnt vmcnt(1)
	v_pk_mul_f32 v[2:3], v[4:5], v[2:3]
	v_pk_mul_f32 v[0:1], v[6:7], v[0:1]
	v_cvt_pk_bf16_f32 v2, v2, v3
	v_cvt_pk_bf16_f32 v3, v0, v1
	v_lshl_add_u64 v[0:1], v[22:23], 0, v[20:21]
	v_add_co_u32_e32 v4, vcc, s3, v0
	global_store_dwordx2 v[50:51], v[2:3], off offset:912
	s_nop 0
	v_addc_co_u32_e32 v5, vcc, 0, v1, vcc
	global_load_ushort v2, v[4:5], off offset:1424
	global_load_ushort v3, v[4:5], off offset:1456
	v_ashrrev_i32_e32 v4, 31, v36
	v_lshrrev_b32_e32 v4, 18, v4
	v_add_u32_e32 v4, v36, v4
	v_and_b32_e32 v4, 0xffffc000, v4
	v_sub_u32_e32 v4, v36, v4
	v_cvt_f32_i32_e32 v4, v4
	v_mul_f32_e32 v4, v43, v4
	v_and_b32_e32 v5, 0x7fffffff, v4
	v_cmp_nlt_f32_e64 s[0:1], |v4|, s18
	s_and_saveexec_b64 s[14:15], s[0:1]
	s_xor_b64 s[14:15], exec, s[14:15]
	s_cbranch_execz .LBB0_425
	v_lshrrev_b32_e32 v6, 23, v5
	v_add_u32_e32 v6, 0xffffff88, v6
	v_cmp_lt_u32_e32 vcc, 63, v6
	v_mov_b32_e32 v23, v137
	v_mov_b32_e32 v25, v137
	v_cndmask_b32_e32 v7, 0, v167, vcc
	v_add_u32_e32 v6, v7, v6
	v_cmp_lt_u32_e64 s[0:1], 31, v6
	v_mov_b32_e32 v27, v137
	v_mov_b32_e32 v29, v137
	v_cndmask_b32_e64 v7, 0, v197, s[0:1]
	v_add_u32_e32 v6, v7, v6
	v_cmp_lt_u32_e64 s[42:43], 31, v6
	v_mov_b32_e32 v31, v137
	v_mov_b32_e32 v33, v137
	v_cndmask_b32_e64 v7, 0, v197, s[42:43]
	v_add_u32_e32 v17, v7, v6
	v_and_b32_e32 v6, 0x7fffff, v5
	v_or_b32_e32 v19, 0x800000, v6
	v_mad_u64_u32 v[6:7], s[16:17], v19, s19, 0
	v_mov_b32_e32 v22, v7
	v_mad_u64_u32 v[22:23], s[16:17], v19, s20, v[22:23]
	v_mov_b32_e32 v24, v23
	v_mad_u64_u32 v[24:25], s[16:17], v19, s21, v[24:25]
	v_mov_b32_e32 v26, v25
	v_mad_u64_u32 v[26:27], s[16:17], v19, s22, v[26:27]
	v_mov_b32_e32 v28, v27
	v_mad_u64_u32 v[28:29], s[16:17], v19, s23, v[28:29]
	v_mov_b32_e32 v30, v29
	v_mad_u64_u32 v[30:31], s[16:17], v19, s26, v[30:31]
	v_mov_b32_e32 v32, v31
	v_mad_u64_u32 v[32:33], s[16:17], v19, s28, v[32:33]
	v_cndmask_b32_e32 v7, v30, v26, vcc
	v_cndmask_b32_e32 v19, v32, v28, vcc
	v_cndmask_b32_e32 v23, v33, v30, vcc
	v_cndmask_b32_e64 v21, v19, v7, s[0:1]
	v_cndmask_b32_e64 v19, v23, v19, s[0:1]
	v_cndmask_b32_e32 v23, v28, v24, vcc
	v_cndmask_b32_e64 v7, v7, v23, s[0:1]
	v_cndmask_b32_e64 v19, v19, v21, s[42:43]
	v_cndmask_b32_e64 v21, v21, v7, s[42:43]
	v_sub_u32_e32 v25, 32, v17
	v_alignbit_b32 v27, v19, v21, v25
	v_cmp_eq_u32_e64 s[44:45], 0, v17
	v_cndmask_b32_e32 v6, v24, v6, vcc
	s_nop 0
	v_cndmask_b32_e64 v17, v27, v19, s[44:45]
	v_cndmask_b32_e32 v19, v26, v22, vcc
	v_cndmask_b32_e64 v22, v23, v19, s[0:1]
	v_cndmask_b32_e64 v7, v7, v22, s[42:43]
	v_alignbit_b32 v23, v21, v7, v25
	v_cndmask_b32_e64 v6, v19, v6, s[0:1]
	v_cndmask_b32_e64 v21, v23, v21, s[44:45]
	v_bfe_u32 v27, v17, 29, 1
	v_cndmask_b32_e64 v6, v22, v6, s[42:43]
	v_alignbit_b32 v23, v17, v21, 30
	v_sub_u32_e32 v28, 0, v27
	v_alignbit_b32 v19, v7, v6, v25
	v_xor_b32_e32 v23, v23, v28
	v_cndmask_b32_e64 v7, v19, v7, s[44:45]
	v_alignbit_b32 v19, v21, v7, 30
	v_ffbh_u32_e32 v21, v23
	v_min_u32_e32 v21, 32, v21
	v_alignbit_b32 v6, v7, v6, 30
	v_xor_b32_e32 v19, v19, v28
	v_sub_u32_e32 v22, 31, v21
	v_xor_b32_e32 v6, v6, v28
	v_alignbit_b32 v23, v23, v19, v22
	v_alignbit_b32 v6, v19, v6, v22
	v_alignbit_b32 v7, v23, v6, 9
	v_ffbh_u32_e32 v19, v7
	v_min_u32_e32 v19, 32, v19
	v_lshrrev_b32_e32 v26, 29, v17
	v_not_b32_e32 v22, v19
	v_alignbit_b32 v6, v7, v6, v22
	v_lshlrev_b32_e32 v7, 31, v26
	v_or_b32_e32 v22, 0x33000000, v7
	v_add_lshl_u32 v19, v19, v21, 23
	v_lshrrev_b32_e32 v6, 9, v6
	v_sub_u32_e32 v19, v22, v19
	v_or_b32_e32 v7, 0.5, v7
	v_lshlrev_b32_e32 v21, 23, v21
	v_or_b32_e32 v6, v19, v6
	v_lshrrev_b32_e32 v19, 9, v23
	v_sub_u32_e32 v7, v7, v21
	v_or_b32_e32 v7, v19, v7
	v_mul_f32_e32 v19, 0x3fc90fda, v7
	v_fma_f32 v21, v7, s29, -v19
	v_fmac_f32_e32 v21, 0x33a22168, v7
	v_fmac_f32_e32 v21, 0x3fc90fda, v6
	v_lshrrev_b32_e32 v7, 30, v17
	v_add_f32_e32 v6, v19, v21
	v_add_u32_e32 v7, v27, v7
	s_andn2_saveexec_b64 s[0:1], s[14:15]
	s_cbranch_execnz .LBB0_426
